# stack2: previous stack + SwiGLU scale folded into the reciprocal + 4-deep p->bf16 prologue loop + mixer K-fragment copies deferred to first reuse
# baseline (speedup 1.0000x reference)
; __device__ __forceinline__ unsigned cvt_pk_bf16(float lo, float hi) { unsigned r; asm volatile("v_cvt_pk_bf16_f32 %0, %1, %2" : "=v"(r) : "v"(lo), "v"(hi)); return r; }
; __device__ __forceinline__ void prologue(const Args& A, LAS unsigned char* lds) {
;     ...
;     const float* p = A.in[I_P]; bf16_t* pb = (bf16_t*)(A.ws + WS_PB);
;     const size_t n8 = (size_t)DEPTH * MTOK * PLE / 8, stride = (size_t)gridDim.x * 512;
;     for (size_t i = (size_t)blockIdx.x * 512 + tid; i < n8; i += stride) {
;         const f32x4 a = *(const f32x4*)(p + i * 8), b = *(const f32x4*)(p + i * 8 + 4);
;         u32x4 w; w.x = pg8::cvt_pk_bf16(a[0], a[1]); w.y = pg8::cvt_pk_bf16(a[2], a[3]); w.z = pg8::cvt_pk_bf16(b[0], b[1]); w.w = pg8::cvt_pk_bf16(b[2], b[3]);
;         *(u32x4*)(pb + i * 8) = w;
;     }
.LBB0_206:
	v_writelane_b32 v254, s83, 21
	s_or_b64 exec, exec, s[8:9]
	s_mov_b32 s83, 0
	s_lshl_b64 s[0:1], s[82:83], 9
	v_ashrrev_i32_e32 v67, 31, v66
	s_waitcnt lgkmcnt(0)
	v_lshl_add_u64 v[2:3], s[0:1], 0, v[66:67]
	s_mov_b64 s[0:1], 0x800000
	v_cmp_gt_u64_e32 vcc, s[0:1], v[2:3]
	s_and_saveexec_b64 s[0:1], vcc
	s_cbranch_execz .LBB0_209
	s_mov_b32 s89, s83
	v_readlane_b32 s8, v254, 4
	s_lshl_b64 s[4:5], s[88:89], 9
	s_lshl_b64 s[6:7], s[82:83], 14
	v_readlane_b32 s10, v254, 6
	v_readlane_b32 s11, v254, 7
	s_add_u32 s6, s10, s6
	v_lshlrev_b64 v[4:5], 5, v[66:67]
	v_readlane_b32 s9, v254, 5
	s_addc_u32 s7, s11, s7
	v_lshl_add_u64 v[4:5], s[6:7], 0, v[4:5]
	s_lshl_b64 s[6:7], s[88:89], 14
	s_lshl_b64 s[8:9], s[82:83], 13
	s_add_u32 s8, s80, s8
	s_addc_u32 s9, s81, s9
	v_readlane_b32 s12, v254, 8
	v_readlane_b32 s13, v254, 9
	v_lshl_add_u64 v[6:7], v[66:67], 4, s[8:9]
	s_mov_b64 s[8:9], 0x30000000
	v_lshl_add_u64 v[4:5], v[4:5], 0, 16
	v_lshl_add_u64 v[6:7], v[6:7], 0, s[8:9]
	s_lshl_b64 s[8:9], s[88:89], 13
	s_mov_b64 s[10:11], 0
	s_mov_b64 s[12:13], 0x7fffff
	v_readlane_b32 s14, v254, 10
	v_readlane_b32 s15, v254, 11
	v_readlane_b32 s16, v254, 12
	v_readlane_b32 s17, v254, 13
	v_readlane_b32 s18, v254, 14
	v_readlane_b32 s19, v254, 15
	v_readlane_b32 s20, v254, 16
	v_readlane_b32 s21, v254, 17
	v_readlane_b32 s22, v254, 18
	v_readlane_b32 s23, v254, 19
	s_cmp_lg_u32 s88, 0x100
	s_cbranch_scc1 .LBB0_208
	s_mov_b32 s100, 14
	global_load_dwordx4 v[8:11], v[4:5], off offset:-16
	global_load_dwordx4 v[12:15], v[4:5], off
	v_lshl_add_u64 v[4:5], v[4:5], 0, s[6:7]
	global_load_dwordx4 v[16:19], v[4:5], off offset:-16
	global_load_dwordx4 v[20:23], v[4:5], off
	v_lshl_add_u64 v[4:5], v[4:5], 0, s[6:7]
	global_load_dwordx4 v[24:27], v[4:5], off offset:-16
	global_load_dwordx4 v[28:31], v[4:5], off
	v_lshl_add_u64 v[4:5], v[4:5], 0, s[6:7]
	global_load_dwordx4 v[32:35], v[4:5], off offset:-16
	global_load_dwordx4 v[36:39], v[4:5], off
	v_lshl_add_u64 v[4:5], v[4:5], 0, s[6:7]
	s_waitcnt vmcnt(6)
	v_cvt_pk_bf16_f32 v8, v8, v9
	v_cvt_pk_bf16_f32 v9, v10, v11
	v_cvt_pk_bf16_f32 v10, v12, v13
	v_cvt_pk_bf16_f32 v11, v14, v15
	global_store_dwordx4 v[6:7], v[8:11], off
	v_lshl_add_u64 v[6:7], v[6:7], 0, s[8:9]
	s_nop 1
	global_load_dwordx4 v[8:11], v[4:5], off offset:-16
	global_load_dwordx4 v[12:15], v[4:5], off
	v_lshl_add_u64 v[4:5], v[4:5], 0, s[6:7]
	s_waitcnt vmcnt(7)
	v_cvt_pk_bf16_f32 v16, v16, v17
	v_cvt_pk_bf16_f32 v17, v18, v19
	v_cvt_pk_bf16_f32 v18, v20, v21
	v_cvt_pk_bf16_f32 v19, v22, v23
	global_store_dwordx4 v[6:7], v[16:19], off
	v_lshl_add_u64 v[6:7], v[6:7], 0, s[8:9]
	s_nop 1
	global_load_dwordx4 v[16:19], v[4:5], off offset:-16
	global_load_dwordx4 v[20:23], v[4:5], off
	v_lshl_add_u64 v[4:5], v[4:5], 0, s[6:7]
	s_waitcnt vmcnt(8)
	v_cvt_pk_bf16_f32 v24, v24, v25
	v_cvt_pk_bf16_f32 v25, v26, v27
	v_cvt_pk_bf16_f32 v26, v28, v29
	v_cvt_pk_bf16_f32 v27, v30, v31
	global_store_dwordx4 v[6:7], v[24:27], off
	v_lshl_add_u64 v[6:7], v[6:7], 0, s[8:9]
	s_nop 1
	global_load_dwordx4 v[24:27], v[4:5], off offset:-16
	global_load_dwordx4 v[28:31], v[4:5], off
	v_lshl_add_u64 v[4:5], v[4:5], 0, s[6:7]
	s_waitcnt vmcnt(9)
	v_cvt_pk_bf16_f32 v32, v32, v33
	v_cvt_pk_bf16_f32 v33, v34, v35
	v_cvt_pk_bf16_f32 v34, v36, v37
	v_cvt_pk_bf16_f32 v35, v38, v39
	global_store_dwordx4 v[6:7], v[32:35], off
	v_lshl_add_u64 v[6:7], v[6:7], 0, s[8:9]
	s_nop 1
	global_load_dwordx4 v[32:35], v[4:5], off offset:-16
	global_load_dwordx4 v[36:39], v[4:5], off
	v_lshl_add_u64 v[4:5], v[4:5], 0, s[6:7]
.Lpconv_loop:
	s_waitcnt vmcnt(9)
	v_cvt_pk_bf16_f32 v8, v8, v9
	v_cvt_pk_bf16_f32 v9, v10, v11
	v_cvt_pk_bf16_f32 v10, v12, v13
	v_cvt_pk_bf16_f32 v11, v14, v15
	global_store_dwordx4 v[6:7], v[8:11], off
	v_lshl_add_u64 v[6:7], v[6:7], 0, s[8:9]
	s_nop 1
	global_load_dwordx4 v[8:11], v[4:5], off offset:-16
	global_load_dwordx4 v[12:15], v[4:5], off
	v_lshl_add_u64 v[4:5], v[4:5], 0, s[6:7]
	s_waitcnt vmcnt(9)
	v_cvt_pk_bf16_f32 v16, v16, v17
	v_cvt_pk_bf16_f32 v17, v18, v19
	v_cvt_pk_bf16_f32 v18, v20, v21
	v_cvt_pk_bf16_f32 v19, v22, v23
	global_store_dwordx4 v[6:7], v[16:19], off
	v_lshl_add_u64 v[6:7], v[6:7], 0, s[8:9]
	s_nop 1
	global_load_dwordx4 v[16:19], v[4:5], off offset:-16
	global_load_dwordx4 v[20:23], v[4:5], off
	v_lshl_add_u64 v[4:5], v[4:5], 0, s[6:7]
	s_waitcnt vmcnt(9)
	v_cvt_pk_bf16_f32 v24, v24, v25
	v_cvt_pk_bf16_f32 v25, v26, v27
	v_cvt_pk_bf16_f32 v26, v28, v29
	v_cvt_pk_bf16_f32 v27, v30, v31
	global_store_dwordx4 v[6:7], v[24:27], off
	v_lshl_add_u64 v[6:7], v[6:7], 0, s[8:9]
	s_nop 1
	global_load_dwordx4 v[24:27], v[4:5], off offset:-16
	global_load_dwordx4 v[28:31], v[4:5], off
	v_lshl_add_u64 v[4:5], v[4:5], 0, s[6:7]
	s_waitcnt vmcnt(9)
	v_cvt_pk_bf16_f32 v32, v32, v33
	v_cvt_pk_bf16_f32 v33, v34, v35
	v_cvt_pk_bf16_f32 v34, v36, v37
	v_cvt_pk_bf16_f32 v35, v38, v39
	global_store_dwordx4 v[6:7], v[32:35], off
	v_lshl_add_u64 v[6:7], v[6:7], 0, s[8:9]
	s_nop 1
	global_load_dwordx4 v[32:35], v[4:5], off offset:-16
	global_load_dwordx4 v[36:39], v[4:5], off
	v_lshl_add_u64 v[4:5], v[4:5], 0, s[6:7]
	s_sub_u32 s100, s100, 1
	s_cmp_lg_u32 s100, 0
	s_cbranch_scc1 .Lpconv_loop
	s_waitcnt vmcnt(9)
	v_cvt_pk_bf16_f32 v8, v8, v9
	v_cvt_pk_bf16_f32 v9, v10, v11
	v_cvt_pk_bf16_f32 v10, v12, v13
	v_cvt_pk_bf16_f32 v11, v14, v15
	global_store_dwordx4 v[6:7], v[8:11], off
	v_lshl_add_u64 v[6:7], v[6:7], 0, s[8:9]
	s_waitcnt vmcnt(7)
	v_cvt_pk_bf16_f32 v16, v16, v17
	v_cvt_pk_bf16_f32 v17, v18, v19
	v_cvt_pk_bf16_f32 v18, v20, v21
	v_cvt_pk_bf16_f32 v19, v22, v23
	global_store_dwordx4 v[6:7], v[16:19], off
	v_lshl_add_u64 v[6:7], v[6:7], 0, s[8:9]
	s_waitcnt vmcnt(5)
	v_cvt_pk_bf16_f32 v24, v24, v25
	v_cvt_pk_bf16_f32 v25, v26, v27
	v_cvt_pk_bf16_f32 v26, v28, v29
	v_cvt_pk_bf16_f32 v27, v30, v31
	global_store_dwordx4 v[6:7], v[24:27], off
	v_lshl_add_u64 v[6:7], v[6:7], 0, s[8:9]
	s_waitcnt vmcnt(3)
	v_cvt_pk_bf16_f32 v32, v32, v33
	v_cvt_pk_bf16_f32 v33, v34, v35
	v_cvt_pk_bf16_f32 v34, v36, v37
	v_cvt_pk_bf16_f32 v35, v38, v39
	global_store_dwordx4 v[6:7], v[32:35], off
	v_lshl_add_u64 v[6:7], v[6:7], 0, s[8:9]
	s_branch .LBB0_209

; #define LAS __attribute__((address_space(3)))
; __device__ __forceinline__ void mixer_attn(const bf16_t* Z, bf16_t* MIX, int b, int r, LAS unsigned char* lds) {
;     ...
;     for (int kr = 0; kr < 8; ++kr) {
;         const int krow = r0 + ((kr - r0) & 7);
;         const bf16_t* kbn = kbb + (size_t)((r0 + ((min(kr + 1, 7) - r0) & 7)) * 64) * NIN;
; #pragma unroll
;         for (int n = 0; n < 8; ++n) { const int ch = lane + 64 * n; *(LAS u32x4*)(wl + (ch >> 3) * VS + 16 * (ch & 7)) = vc[n]; }
;         asm volatile("" ::: "memory");
; #pragma unroll
;         for (int n = 0; n < 8; ++n) vc[n] = LDV(kbn, n);
;         asm volatile("" ::: "memory");
;         LAS const float* brow = btab + (krow - r + 7) * 31 - 1 + c0;
;         bf16x8 pf[6];
;         bf16x8 dummy;
;         f32x4 sA[3], sB[3]; float bA[3][4], bB[3][4];
;         qk<0>(kf, qlds, brow, sA, bA);
;         qk<1>(kf, qlds, brow, sB, bB);
;         sm<0>(sA, bA, m0[0], mrun[0], lrun[0], o[0], pf[0], dummy);
.LBB0_289:
	s_add_i32 s84, s33, 1
	s_min_u32 s67, s84, 7
	s_sub_i32 s67, s67, s1
	s_and_b32 s67, s67, 7
	s_add_i32 s67, s67, s1
	s_add_i32 s66, s85, s33
	s_mul_i32 s67, s67, 0x60000
	s_add_u32 s68, s82, s67
	s_addc_u32 s69, s93, 0
	s_mov_b64 s[100:101], s[68:69]
	s_waitcnt vmcnt(9)
	ds_write_b128 v212, v[104:107]
	ds_write_b128 v212, v[96:99] offset:1152
	ds_write_b128 v212, v[100:103] offset:2304
	ds_write_b128 v212, v[108:111] offset:3456
	ds_write_b128 v212, v[112:115] offset:4608
	ds_write_b128 v212, v[116:119] offset:5760
	ds_write_b128 v212, v[120:123] offset:6912
	s_waitcnt vmcnt(8)
	ds_write_b128 v212, v[124:127] offset:8064
	s_and_b32 s66, s66, 7
	v_lshl_add_u64 v[96:97], s[68:69], 0, v[160:161]
	s_add_i32 s76, s2, s66
	v_add_co_u32_e64 v98, s[66:67], s77, v96
	v_add_co_u32_e64 v100, s[68:69], s3, v96
	s_nop 0
	v_addc_co_u32_e64 v99, s[66:67], 0, v97, s[66:67]
	v_addc_co_u32_e64 v101, s[68:69], 0, v97, s[68:69]
	v_add_co_u32_e64 v108, s[70:71], s94, v96
	v_add_co_u32_e64 v112, s[72:73], s78, v96
	v_add_co_u32_e64 v116, s[74:75], s95, v96
	v_add_co_u32_e64 v120, s[66:67], s79, v96
	v_add_co_u32_e64 v124, s[68:69], s99, v96
	v_addc_co_u32_e64 v109, s[70:71], 0, v97, s[70:71]
	v_addc_co_u32_e64 v113, s[72:73], 0, v97, s[72:73]
	v_addc_co_u32_e64 v117, s[74:75], 0, v97, s[74:75]
	v_addc_co_u32_e64 v121, s[66:67], 0, v97, s[66:67]
	v_addc_co_u32_e64 v125, s[66:67], 0, v97, s[68:69]
	global_load_dwordx4 v[104:107], v[96:97], off offset:2048
	s_nop 0
	global_load_dwordx4 v[96:99], v[98:99], off offset:2048
	s_nop 0
	global_load_dwordx4 v[100:103], v[100:101], off offset:2048
	s_nop 0
	global_load_dwordx4 v[108:111], v[108:109], off offset:2048
	s_nop 0
	global_load_dwordx4 v[112:115], v[112:113], off offset:2048
	s_nop 0
	global_load_dwordx4 v[116:119], v[116:117], off offset:2048
	s_nop 0
	global_load_dwordx4 v[120:123], v[120:121], off offset:2048
	s_nop 0
	global_load_dwordx4 v[124:127], v[124:125], off offset:2048
	s_cmp_eq_u32 s33, 0
	s_cbranch_scc1 .Lkr_first
	s_waitcnt vmcnt(8)
	v_mov_b64_e32 v[92:93], v[128:129]
	v_mov_b64_e32 v[94:95], v[130:131]
	v_mov_b64_e32 v[80:81], v[132:133]
	v_mov_b64_e32 v[82:83], v[134:135]
	v_mov_b64_e32 v[56:57], v[136:137]
	v_mov_b64_e32 v[58:59], v[138:139]
	v_mov_b64_e32 v[52:53], v[140:141]
	v_mov_b64_e32 v[54:55], v[142:143]
.Lkr_first:
	v_lshl_add_u64 v[128:129], s[100:101], 0, v[156:157]
	ds_read_b128 v[132:135], v210 offset:11520
	s_mulk_i32 s76, 0x7c
	v_add_u32_e32 v142, s76, v211
	v_add_u32_e32 v165, 0x2860, v142
	v_add_u32_e32 v200, 0x28a0, v142
	v_add_u32_e32 v202, 0x28a8, v142
	s_waitcnt vmcnt(15) lgkmcnt(0)
	v_mfma_f32_16x16x32_bf16 v[138:141], v[40:43], v[132:135], 0
	v_add_u32_e32 v174, 0x28e0, v142
	v_add_u32_e32 v176, 0x28e8, v142
	v_add_u32_e32 v194, 0x2868, v142
	ds_read_b128 v[142:145], v210 offset:13568
	ds_read_b128 v[146:149], v210 offset:12544
	ds_read_b128 v[150:153], v210 offset:14592
	s_waitcnt vmcnt(13)
	v_mfma_f32_16x16x32_bf16 v[132:135], v[32:35], v[132:135], 0
	ds_read2_b32 v[154:155], v200 offset1:1
	ds_read2_b32 v[170:171], v202 offset1:1
	ds_read2_b32 v[172:173], v174 offset1:1
	ds_read2_b32 v[180:181], v165 offset1:1
	ds_read2_b32 v[186:187], v176 offset1:1
	ds_read2_b32 v[188:189], v194 offset1:1
	v_add_co_u32_e64 v130, s[70:71], s3, v128
	s_waitcnt lgkmcnt(7)
	v_mfma_f32_16x16x32_bf16 v[138:141], v[36:39], v[146:149], v[138:141]
	s_waitcnt lgkmcnt(3)
	v_mov_b32_e32 v175, v173
	v_mov_b32_e32 v177, v154
	s_waitcnt lgkmcnt(1)
	v_mov_b32_e32 v178, v187
	v_mfma_f32_16x16x32_bf16 v[40:43], v[40:43], v[142:145], 0
	v_mov_b32_e32 v179, v170
	v_mov_b32_e32 v182, v172
	v_mov_b32_e32 v183, v186
	v_mfma_f32_16x16x32_bf16 v[166:169], v[32:35], v[142:145], 0
	v_mov_b32_e32 v195, v171
	v_add_co_u32_e64 v184, s[72:73], s78, v128
	s_waitcnt vmcnt(8)
	v_mfma_f32_16x16x32_bf16 v[142:145], v[20:23], v[142:145], 0
	v_add_co_u32_e64 v136, s[74:75], s79, v128
	v_addc_co_u32_e64 v131, s[66:67], 0, v129, s[70:71]
	v_mfma_f32_16x16x32_bf16 v[132:135], v[92:95], v[146:149], v[132:135]
	v_mov_b32_e32 v146, v155
	v_mov_b32_e32 v147, v171
	v_mfma_f32_16x16x32_bf16 v[36:39], v[36:39], v[150:153], v[40:43]
	v_add_f32_e32 v138, v138, v177
	v_add_f32_e32 v139, v139, v146
	v_add_f32_e32 v140, v140, v179
	v_add_f32_e32 v141, v141, v147
	v_cndmask_b32_e32 v138, v235, v138, vcc
	v_cndmask_b32_e64 v139, v235, v139, s[4:5]
	v_mfma_f32_16x16x32_bf16 v[40:43], v[92:95], v[150:153], v[166:169]
	v_add_f32_e32 v132, v132, v182
	v_add_f32_e32 v133, v133, v175
	v_cndmask_b32_e64 v140, v235, v140, s[6:7]
	s_waitcnt vmcnt(10)
	v_mfma_f32_16x16x32_bf16 v[148:151], v[56:59], v[150:153], v[142:145]
	v_cndmask_b32_e64 v141, v235, v141, s[8:9]
	v_add_f32_e32 v134, v134, v183
	v_add_f32_e32 v135, v135, v178
	v_max3_f32 v142, v138, s98, v139
	v_cndmask_b32_e64 v132, v235, v132, s[10:11]
	v_cndmask_b32_e64 v133, v235, v133, s[12:13]
	v_max3_f32 v142, v142, v140, v141
	v_cndmask_b32_e64 v134, v235, v134, s[14:15]
	v_cndmask_b32_e64 v135, v235, v135, s[16:17]
	v_max3_f32 v142, v142, v132, v133
	v_max3_f32 v142, v142, v134, v135
	v_mov_b32_e32 v143, v142
	s_nop 1
	v_permlane16_swap_b32_e32 v142, v143
	v_max_f32_e32 v143, v143, v143
	v_max_f32_e32 v142, v142, v142
	v_max_f32_e32 v142, v142, v143
	v_mov_b32_e32 v143, v142
	s_nop 1
	v_permlane32_swap_b32_e32 v142, v143
	v_max3_f32 v142, v214, v142, v143
	v_sub_f32_e32 v143, v214, v142
	v_sub_f32_e32 v138, v138, v142
	v_sub_f32_e32 v139, v139, v142
	v_sub_f32_e32 v140, v140, v142
	v_sub_f32_e32 v141, v141, v142
	v_sub_f32_e32 v132, v132, v142
	v_sub_f32_e32 v133, v133, v142
	v_sub_f32_e32 v134, v134, v142
	v_sub_f32_e32 v135, v135, v142
	v_mov_b32_e32 v214, v142
	v_exp_f32_e32 v142, v143
	s_waitcnt lgkmcnt(0)
; __device__ __forceinline__ void mixer_attn(const bf16_t* Z, bf16_t* MIX, int b, int r, LAS unsigned char* lds) {
;     ...
;         qk<0>(kf, qlds, brow, sA, bA);
;         qk<1>(kf, qlds, brow, sB, bB);
;         sm<0>(sA, bA, m0[0], mrun[0], lrun[0], o[0], pf[0], dummy);
;         qk<2>(kf, qlds, brow, sA, bA);
;         sm<1>(sB, bB, m0[1], mrun[1], lrun[1], o[1], pf[1], pf[2]);
;         qk<3>(kf, qlds, brow, sB, bB);
;         asm volatile("" ::: "memory");
; #pragma unroll
;         for (int kt = 0; kt < 4; ++kt)
; #pragma unroll
;             for (int dh = 0; dh < 2; ++dh) kf[kt][dh] = LDK(kbn, kt, dh);
	v_mov_b32_e32 v166, v188
	v_mov_b32_e32 v168, v173
	v_exp_f32_e32 v183, v138
	v_exp_f32_e32 v179, v139
	v_exp_f32_e32 v177, v140
	v_exp_f32_e32 v175, v141
	v_exp_f32_e32 v169, v132
	v_exp_f32_e32 v173, v133
	v_exp_f32_e32 v171, v134
	v_exp_f32_e32 v167, v135
	v_cvt_pk_bf16_f32 v144, v183, v179
	v_cvt_pk_bf16_f32 v145, v177, v175
	v_cvt_pk_bf16_f32 v146, v169, v173
	v_cvt_pk_bf16_f32 v147, v171, v167
	ds_read_b128 v[132:135], v210 offset:15616
	ds_read_b128 v[138:141], v210 offset:16640
	ds_read2_b32 v[190:191], v165 offset1:1
	ds_read2_b32 v[206:207], v200 offset1:1
	ds_read2_b32 v[230:231], v202 offset1:1
	ds_read2_b32 v[246:247], v174 offset1:1
	ds_read2_b32 v[248:249], v194 offset1:1
	ds_read2_b32 v[250:251], v176 offset1:1
	v_pk_mul_f32 v[50:51], v[50:51], v[142:143] op_sel_hi:[1,0]
	v_add_f32_e32 v36, v36, v180
	v_add_f32_e32 v37, v37, v181
	v_pk_mul_f32 v[48:49], v[48:49], v[142:143] op_sel_hi:[1,0]
	v_pk_mul_f32 v[70:71], v[70:71], v[142:143] op_sel_hi:[1,0]
	v_pk_mul_f32 v[68:69], v[68:69], v[142:143] op_sel_hi:[1,0]
	v_pk_mul_f32 v[78:79], v[78:79], v[142:143] op_sel_hi:[1,0]
	v_pk_mul_f32 v[76:77], v[76:77], v[142:143] op_sel_hi:[1,0]
	v_pk_mul_f32 v[90:91], v[90:91], v[142:143] op_sel_hi:[1,0]
	v_pk_mul_f32 v[88:89], v[88:89], v[142:143] op_sel_hi:[1,0]
	v_add_f32_e32 v38, v38, v166
	v_add_f32_e32 v39, v39, v189
	v_add_f32_e32 v40, v40, v154
	v_add_f32_e32 v143, v148, v172
	v_add_f32_e32 v148, v149, v168
	v_add_f32_e32 v149, v150, v186
	v_add_f32_e32 v150, v151, v187
	v_cndmask_b32_e64 v151, v235, v36, s[18:19]
	v_cndmask_b32_e64 v152, v235, v37, s[20:21]
	s_waitcnt lgkmcnt(7)
	v_mfma_f32_16x16x32_bf16 v[32:35], v[32:35], v[132:135], 0
	v_add_f32_e32 v41, v41, v155
	v_cndmask_b32_e64 v153, v235, v38, s[22:23]
	v_cndmask_b32_e64 v154, v235, v39, s[24:25]
	v_cndmask_b32_e64 v155, v235, v40, s[26:27]
	v_max3_f32 v40, v151, s98, v152
	v_add_f32_e32 v42, v42, v170
	v_add_f32_e32 v43, v43, v195
	v_cndmask_b32_e64 v166, v235, v41, s[28:29]
	v_max3_f32 v40, v40, v153, v154
	v_cndmask_b32_e64 v168, v235, v42, s[30:31]
	v_cndmask_b32_e64 v170, v235, v43, s[34:35]
	v_max3_f32 v172, v40, v155, v166
	v_cndmask_b32_e64 v143, v235, v143, s[36:37]
	v_cndmask_b32_e64 v148, v235, v148, s[38:39]
	s_waitcnt lgkmcnt(6)
	v_mfma_f32_16x16x32_bf16 v[186:189], v[92:95], v[138:141], v[32:35]
	v_cndmask_b32_e64 v149, v235, v149, s[40:41]
	v_cndmask_b32_e64 v150, v235, v150, s[42:43]
	s_waitcnt lgkmcnt(1)
	v_mov_b32_e32 v204, v248
	v_max3_f32 v32, v172, v168, v170
	v_max3_f32 v32, v32, v143, v148
	v_max3_f32 v32, v32, v149, v150
	v_mov_b32_e32 v33, v32
	s_nop 1
	v_permlane16_swap_b32_e32 v32, v33
	v_max_f32_e32 v33, v33, v33
	v_max_f32_e32 v32, v32, v32
	v_max_f32_e32 v32, v32, v33
	v_mov_b32_e32 v33, v32
	s_nop 1
	v_permlane32_swap_b32_e32 v32, v33
	v_mfma_f32_16x16x32_bf16 v[36:39], v[20:23], v[132:135], 0
	v_max3_f32 v32, v215, v32, v33
	v_sub_f32_e32 v33, v215, v32
	v_exp_f32_e32 v180, v33
	s_waitcnt vmcnt(9)
	v_mfma_f32_16x16x32_bf16 v[40:43], v[80:83], v[132:135], 0
	v_sub_f32_e32 v34, v151, v32
	v_sub_f32_e32 v35, v152, v32
	v_sub_f32_e32 v92, v149, v32
	v_mfma_f32_16x16x32_bf16 v[218:221], v[56:59], v[138:141], v[36:39]
	v_sub_f32_e32 v93, v150, v32
	v_mov_b32_e32 v215, v32
	v_mov_b32_e32 v217, v247
	s_waitcnt vmcnt(8)
	v_mfma_f32_16x16x32_bf16 v[222:225], v[52:55], v[138:141], v[40:43]
	v_sub_f32_e32 v36, v153, v32
	v_sub_f32_e32 v37, v154, v32
	v_sub_f32_e32 v38, v155, v32
	v_sub_f32_e32 v39, v166, v32
	v_sub_f32_e32 v40, v168, v32
	v_sub_f32_e32 v41, v170, v32
	v_sub_f32_e32 v42, v143, v32
	v_sub_f32_e32 v43, v148, v32
	v_exp_f32_e32 v32, v34
	s_waitcnt lgkmcnt(0)
	v_mov_b32_e32 v237, v251
	v_exp_f32_e32 v247, v35
	v_exp_f32_e32 v248, v36
	v_exp_f32_e32 v251, v37
	v_exp_f32_e32 v182, v38
	v_exp_f32_e32 v178, v39
	v_exp_f32_e32 v176, v40
	v_exp_f32_e32 v174, v41
	v_exp_f32_e32 v168, v42
	v_exp_f32_e32 v172, v43
	v_exp_f32_e32 v170, v92
	v_exp_f32_e32 v166, v93
	v_pk_mul_f32 v[154:155], v[86:87], v[180:181] op_sel_hi:[1,0]
	v_pk_mul_f32 v[152:153], v[84:85], v[180:181] op_sel_hi:[1,0]
	v_cvt_pk_bf16_f32 v84, v32, v247
	v_cvt_pk_bf16_f32 v85, v248, v251
	v_cvt_pk_bf16_f32 v86, v182, v178
	v_cvt_pk_bf16_f32 v87, v176, v174
	v_cvt_pk_bf16_f32 v92, v168, v172
	v_cvt_pk_bf16_f32 v93, v170, v166
	v_cvt_pk_bf16_f32 v94, v193, v193
	v_cvt_pk_bf16_f32 v95, v193, v193
	ds_read_b128 v[226:229], v210 offset:17664
	ds_read_b128 v[238:241], v210 offset:18688
	ds_read2_b32 v[252:253], v165 offset1:1
	ds_read2_b32 v[194:195], v194 offset1:1
	ds_read2_b32 v[200:201], v200 offset1:1
	ds_read2_b32 v[202:203], v202 offset1:1
	s_waitcnt lgkmcnt(5)
	v_mfma_f32_16x16x32_bf16 v[242:245], v[20:23], v[226:229], 0
	v_addc_co_u32_e64 v185, s[66:67], 0, v129, s[72:73]
	v_addc_co_u32_e64 v137, s[66:67], 0, v129, s[74:75]
	v_mfma_f32_16x16x32_bf16 v[80:83], v[80:83], v[226:229], 0
	v_mul_f32_e64 v150, v74, v180
	v_mul_f32_e64 v151, v75, v180
	v_pk_mul_f32 v[148:149], v[72:73], v[180:181] op_sel_hi:[1,0]
	v_pk_mul_f32 v[74:75], v[66:67], v[180:181] op_sel_hi:[1,0]
	v_pk_mul_f32 v[72:73], v[64:65], v[180:181] op_sel_hi:[1,0]
	v_pk_mul_f32 v[62:63], v[62:63], v[180:181] op_sel_hi:[1,0]
	v_pk_mul_f32 v[60:61], v[60:61], v[180:181] op_sel_hi:[1,0]
	v_add_f32_e32 v64, 0, v32
	v_mov_b32_e32 v181, v142
	global_load_dwordx4 v[40:43], v[128:129], off offset:1024
	global_load_dwordx4 v[36:39], v[128:129], off offset:1088
	global_load_dwordx4 v[32:35], v[130:131], off offset:1024
	s_nop 0
	global_load_dwordx4 v[128:131], v[130:131], off offset:1088
	s_nop 0
	global_load_dwordx4 v[132:135], v[136:137], off offset:1024
	global_load_dwordx4 v[140:143], v[136:137], off offset:1088
	s_nop 0
	global_load_dwordx4 v[136:139], v[184:185], off offset:1088
	global_load_dwordx4 v[20:23], v[184:185], off offset:1024
	s_waitcnt lgkmcnt(2)
; __device__ __forceinline__ v4i16_t vtr(LAS unsigned char* p) { return __builtin_amdgcn_ds_read_tr16_b64_v4i16((LAS v4i16_t*)p); }
; __device__ __forceinline__ void mixer_attn(const bf16_t* Z, bf16_t* MIX, int b, int r, LAS unsigned char* lds) {
;     ...
;         sm<2>(sA, bA, m0[2], mrun[2], lrun[2], o[2], pf[3], pf[4]);
;         sm<3>(sB, bB, m0[3], mrun[3], lrun[3], o[3], dummy, pf[5]);
; #pragma unroll
;         for (int dt = 0; dt < 4; ++dt) {
;             const bf16x8 a01 = cat8(vtr(vrd + 32 * dt), vtr(vrd + 16 * VS + 32 * dt)), a23 = cat8(vtr(vrd + 32 * VS + 32 * dt), vtr(vrd + 48 * VS + 32 * dt));
;             o[0][dt] = __builtin_amdgcn_mfma_f32_16x16x32_bf16(a01, pf[0], o[0][dt], 0, 0, 0);
;             o[1][dt] = __builtin_amdgcn_mfma_f32_16x16x32_bf16(a01, pf[1], o[1][dt], 0, 0, 0);
;             o[1][dt] = __builtin_amdgcn_mfma_f32_16x16x32_bf16(a23, pf[2], o[1][dt], 0, 0, 0);
;             o[2][dt] = __builtin_amdgcn_mfma_f32_16x16x32_bf16(a01, pf[3], o[2][dt], 0, 0, 0);
;             o[2][dt] = __builtin_amdgcn_mfma_f32_16x16x32_bf16(a23, pf[4], o[2][dt], 0, 0, 0);
;             o[3][dt] = __builtin_amdgcn_mfma_f32_16x16x32_bf16(a23, pf[5], o[3][dt], 0, 0, 0);
	v_mov_b32_e32 v184, v195
	v_add_f32_e32 v66, v187, v191
	v_add_f32_e32 v185, v186, v190
	v_add_f32_e32 v67, v189, v249
	v_add_f32_e32 v186, v188, v204
	v_cndmask_b32_e64 v185, v235, v185, s[44:45]
	v_cndmask_b32_e64 v66, v235, v66, s[20:21]
	v_add_f32_e32 v187, v218, v206
	v_add_f32_e32 v189, v219, v207
	v_add_f32_e32 v190, v220, v230
	v_add_f32_e32 v191, v221, v231
	v_cndmask_b32_e64 v186, v235, v186, s[22:23]
	v_cndmask_b32_e64 v67, v235, v67, s[24:25]
	v_mfma_f32_16x16x32_bf16 v[218:221], v[56:59], v[238:241], v[242:245]
	v_max3_f32 v58, v185, s98, v66
	s_waitcnt lgkmcnt(0)
	v_mov_b32_e32 v188, v203
	v_add_f32_e32 v203, v222, v246
	v_add_f32_e32 v204, v223, v217
	v_add_f32_e32 v206, v224, v250
	v_add_f32_e32 v207, v225, v237
	v_cndmask_b32_e64 v187, v235, v187, s[46:47]
	v_cndmask_b32_e64 v189, v235, v189, s[28:29]
	v_mfma_f32_16x16x32_bf16 v[222:225], v[52:55], v[238:241], v[80:83]
	v_max3_f32 v52, v58, v186, v67
	v_cndmask_b32_e64 v190, v235, v190, s[30:31]
	v_cndmask_b32_e64 v191, v235, v191, s[34:35]
	v_max3_f32 v52, v52, v187, v189
	v_cndmask_b32_e64 v203, v235, v203, s[48:49]
	v_cndmask_b32_e64 v204, v235, v204, s[38:39]
	v_max3_f32 v52, v52, v190, v191
	v_cndmask_b32_e64 v56, v235, v206, s[40:41]
	v_cndmask_b32_e64 v57, v235, v207, s[42:43]
	v_max3_f32 v52, v52, v203, v204
	v_max3_f32 v52, v52, v56, v57
	v_mov_b32_e32 v53, v52
	s_nop 1
	v_permlane16_swap_b32_e32 v52, v53
	v_max_f32_e32 v53, v53, v53
	v_max_f32_e32 v52, v52, v52
	v_max_f32_e32 v52, v52, v53
	v_mov_b32_e32 v53, v52
	s_nop 1
	v_permlane32_swap_b32_e32 v52, v53
	v_max3_f32 v207, v216, v52, v53
	v_sub_f32_e32 v52, v216, v207
	v_sub_f32_e32 v82, v204, v207
	v_exp_f32_e32 v204, v52
	v_mov_b32_e32 v195, v201
	v_mov_b32_e32 v201, v252
	v_sub_f32_e32 v53, v185, v207
	v_sub_f32_e32 v54, v66, v207
	v_sub_f32_e32 v55, v186, v207
	v_sub_f32_e32 v58, v67, v207
	v_sub_f32_e32 v59, v187, v207
	v_sub_f32_e32 v66, v189, v207
	v_sub_f32_e32 v67, v190, v207
	v_sub_f32_e32 v80, v191, v207
	v_sub_f32_e32 v81, v203, v207
	v_sub_f32_e32 v56, v56, v207
	v_sub_f32_e32 v57, v57, v207
	v_add_f32_e32 v165, v247, v64
	v_cvt_pk_bf16_f32 v64, v193, v193
	v_cvt_pk_bf16_f32 v65, v193, v193
	v_exp_f32_e32 v203, v53
	v_exp_f32_e32 v237, v54
	v_exp_f32_e32 v246, v55
	v_exp_f32_e32 v247, v58
	v_exp_f32_e32 v191, v59
	v_exp_f32_e32 v189, v66
	v_exp_f32_e32 v187, v67
	v_exp_f32_e32 v83, v80
	v_exp_f32_e32 v81, v81
	v_exp_f32_e32 v185, v82
	v_exp_f32_e32 v59, v56
	v_exp_f32_e32 v57, v57
	v_pk_mul_f32 v[226:227], v[44:45], v[204:205] op_sel_hi:[1,0]
	v_cvt_pk_bf16_f32 v66, v203, v237
	v_cvt_pk_bf16_f32 v67, v246, v247
	v_cvt_pk_bf16_f32 v52, v191, v189
	v_cvt_pk_bf16_f32 v53, v187, v83
	v_cvt_pk_bf16_f32 v54, v81, v185
	v_cvt_pk_bf16_f32 v55, v59, v57
	v_pk_mul_f32 v[228:229], v[46:47], v[204:205] op_sel_hi:[1,0]
	v_add_f32_e32 v44, v218, v201
	v_add_f32_e32 v45, v219, v253
	v_add_f32_e32 v46, v220, v194
	v_add_f32_e32 v47, v221, v184
	v_cndmask_b32_e64 v44, v235, v44, s[50:51]
	v_cndmask_b32_e64 v45, v235, v45, s[52:53]
	v_add_f32_e32 v56, v222, v200
	v_add_f32_e32 v58, v223, v195
	v_cndmask_b32_e64 v46, v235, v46, s[54:55]
	v_cndmask_b32_e64 v47, v235, v47, s[56:57]
	v_max3_f32 v184, v44, s98, v45
	v_add_f32_e32 v80, v224, v202
	v_add_f32_e32 v82, v225, v188
	v_cndmask_b32_e64 v56, v235, v56, s[58:59]
	v_cndmask_b32_e64 v58, v235, v58, s[60:61]
	v_max3_f32 v184, v184, v46, v47
	v_cndmask_b32_e64 v80, v235, v80, s[62:63]
	v_cndmask_b32_e64 v82, v235, v82, s[64:65]
	v_max3_f32 v184, v184, v56, v58
	v_max3_f32 v184, v184, v80, v82
	v_mov_b32_e32 v186, v184
	s_nop 1
	v_permlane16_swap_b32_e32 v184, v186
	v_max_f32_e32 v186, v186, v186
	v_max_f32_e32 v184, v184, v184
	v_max_f32_e32 v184, v184, v186
	v_mov_b32_e32 v186, v184
	s_nop 1
	v_permlane32_swap_b32_e32 v184, v186
	v_max3_f32 v194, v192, v184, v186
	v_sub_f32_e32 v44, v44, v194
	v_sub_f32_e32 v45, v45, v194
	v_sub_f32_e32 v46, v46, v194
	v_sub_f32_e32 v47, v47, v194
	v_sub_f32_e32 v56, v56, v194
	v_sub_f32_e32 v58, v58, v194
	v_sub_f32_e32 v195, v80, v194
	v_sub_f32_e32 v200, v82, v194
	v_exp_f32_e32 v190, v44
	v_exp_f32_e32 v188, v45
	v_exp_f32_e32 v186, v46
	v_exp_f32_e32 v82, v47
	v_exp_f32_e32 v80, v56
	v_exp_f32_e32 v184, v58
	v_exp_f32_e32 v58, v195
	v_exp_f32_e32 v56, v200
	v_cvt_pk_bf16_f32 v44, v190, v188
	v_cvt_pk_bf16_f32 v45, v186, v82
	v_cvt_pk_bf16_f32 v46, v80, v184
	v_cvt_pk_bf16_f32 v47, v58, v56
	ds_read_b64_tr_b16 v[218:219], v213 offset:2304
	ds_read_b64_tr_b16 v[216:217], v213
	s_waitcnt lgkmcnt(0)
	v_mfma_f32_16x16x32_bf16 v[48:51], v[216:219], v[144:147], v[48:51]
	ds_read_b64_tr_b16 v[220:221], v213 offset:4608
	ds_read_b64_tr_b16 v[222:223], v213 offset:6912
	ds_read_b64_tr_b16 v[224:225], v213 offset:32
	v_mfma_f32_16x16x32_bf16 v[152:155], v[216:219], v[84:87], v[152:155]
	v_mul_f32_e64 v30, v30, v204
	v_mul_f32_e64 v31, v31, v204
	v_pk_mul_f32 v[28:29], v[28:29], v[204:205] op_sel_hi:[1,0]
	ds_read_b64_tr_b16 v[230:231], v213 offset:6944
	v_mfma_f32_16x16x32_bf16 v[216:219], v[216:219], v[64:67], v[226:229]
	ds_read_b64_tr_b16 v[238:239], v213 offset:4672
	ds_read_b64_tr_b16 v[240:241], v213 offset:6976
	v_sub_f32_e32 v192, v192, v194
	ds_read_b64_tr_b16 v[226:227], v213 offset:2336
	s_waitcnt lgkmcnt(0)
	v_mfma_f32_16x16x32_bf16 v[68:71], v[224:227], v[144:147], v[68:71]
	ds_read_b64_tr_b16 v[228:229], v213 offset:4640
	v_exp_f32_e32 v206, v192
	v_pk_mul_f32 v[26:27], v[26:27], v[204:205] op_sel_hi:[1,0]
	v_mfma_f32_16x16x32_bf16 v[148:151], v[224:227], v[84:87], v[148:151]
	v_mul_f32_e64 v24, v24, v204
	v_mul_f32_e64 v25, v25, v204
	v_pk_mul_f32 v[14:15], v[14:15], v[206:207] op_sel_hi:[1,0]
	v_pk_mul_f32 v[12:13], v[12:13], v[206:207] op_sel_hi:[1,0]
	v_mfma_f32_16x16x32_bf16 v[28:31], v[224:227], v[64:67], v[28:31]
	ds_read_b64_tr_b16 v[224:225], v213 offset:64
	ds_read_b64_tr_b16 v[226:227], v213 offset:2368
	v_pk_mul_f32 v[10:11], v[10:11], v[206:207] op_sel_hi:[1,0]
	s_waitcnt lgkmcnt(0)
; __device__ __forceinline__ v4i16_t vtr(LAS unsigned char* p) { return __builtin_amdgcn_ds_read_tr16_b64_v4i16((LAS v4i16_t*)p); }
; __device__ __forceinline__ void mixer_attn(const bf16_t* Z, bf16_t* MIX, int b, int r, LAS unsigned char* lds) {
;     ...
;         for (int dt = 0; dt < 4; ++dt) {
;             const bf16x8 a01 = cat8(vtr(vrd + 32 * dt), vtr(vrd + 16 * VS + 32 * dt)), a23 = cat8(vtr(vrd + 32 * VS + 32 * dt), vtr(vrd + 48 * VS + 32 * dt));
;             o[0][dt] = __builtin_amdgcn_mfma_f32_16x16x32_bf16(a01, pf[0], o[0][dt], 0, 0, 0);
;             o[1][dt] = __builtin_amdgcn_mfma_f32_16x16x32_bf16(a01, pf[1], o[1][dt], 0, 0, 0);
;             o[1][dt] = __builtin_amdgcn_mfma_f32_16x16x32_bf16(a23, pf[2], o[1][dt], 0, 0, 0);
;             o[2][dt] = __builtin_amdgcn_mfma_f32_16x16x32_bf16(a01, pf[3], o[2][dt], 0, 0, 0);
;             o[2][dt] = __builtin_amdgcn_mfma_f32_16x16x32_bf16(a23, pf[4], o[2][dt], 0, 0, 0);
;             o[3][dt] = __builtin_amdgcn_mfma_f32_16x16x32_bf16(a23, pf[5], o[3][dt], 0, 0, 0);
;         }
;     }
; #pragma unroll
;     for (int jq = 0; jq < 4; ++jq) {
;         const float lt = xrow16_sum(lrun[jq]);
;         const float inv = 1.0f / lt; float ss = 0.f;
; #pragma unroll
;         for (int dt = 0; dt < 4; ++dt) { o[jq][dt] *= inv; ss += (o[jq][dt][0] * o[jq][dt][0] + o[jq][dt][1] * o[jq][dt][1]) + (o[jq][dt][2] * o[jq][dt][2] + o[jq][dt][3] * o[jq][dt][3]); }
;         ss = xrow16_sum(ss);
;         if (g == 0) ssbuf[h * 64 + 16 * jq + i] = ss;
	v_mfma_f32_16x16x32_bf16 v[242:245], v[224:227], v[84:87], v[72:75]
	s_nop 2
	ds_read_b64_tr_b16 v[72:73], v213 offset:96
	ds_read_b64_tr_b16 v[74:75], v213 offset:2400
	v_pk_mul_f32 v[8:9], v[8:9], v[206:207] op_sel_hi:[1,0]
	v_mfma_f32_16x16x32_bf16 v[76:79], v[224:227], v[144:147], v[76:79]
	v_mul_f32_e64 v6, v6, v206
	v_mul_f32_e64 v7, v7, v206
	v_pk_mul_f32 v[4:5], v[4:5], v[206:207] op_sel_hi:[1,0]
	v_pk_mul_f32 v[2:3], v[2:3], v[206:207] op_sel_hi:[1,0]
	s_waitcnt lgkmcnt(0)
	v_mfma_f32_16x16x32_bf16 v[88:91], v[72:75], v[144:147], v[88:91]
	v_add_f32_e32 v144, v248, v165
	v_add_f32_e32 v192, v251, v144
	ds_read_b64_tr_b16 v[144:145], v213 offset:4704
	ds_read_b64_tr_b16 v[146:147], v213 offset:7008
	v_pk_add_f32 v[182:183], v[182:183], v[192:193]
	v_pk_mul_f32 v[0:1], v[0:1], v[206:207] op_sel_hi:[1,0]
	v_mfma_f32_16x16x32_bf16 v[12:15], v[220:223], v[44:47], v[12:15]
	v_mul_f32_e64 v18, v18, v204
	v_mul_f32_e64 v19, v19, v204
	v_pk_mul_f32 v[16:17], v[16:17], v[204:205] op_sel_hi:[1,0]
	v_mov_b32_e32 v164, v193
	v_mfma_f32_16x16x32_bf16 v[8:11], v[228:231], v[44:47], v[8:11]
	s_mov_b32 s33, s84
	s_cmp_eq_u32 s84, 8
	v_mov_b32_e32 v192, v194
	v_mfma_f32_16x16x32_bf16 v[4:7], v[238:241], v[44:47], v[4:7]
	s_waitcnt lgkmcnt(0)
	v_mfma_f32_16x16x32_bf16 v[0:3], v[144:147], v[44:47], v[0:3]
	v_add_f32_e64 v44, v178, v182
	v_add_f32_e64 v45, v179, v183
	v_pk_add_f32 v[44:45], v[176:177], v[44:45]
	v_mfma_f32_16x16x32_bf16 v[24:27], v[224:227], v[64:67], v[24:27]
	v_add_f32_e64 v44, v174, v44
	v_add_f32_e64 v45, v175, v45
	v_pk_add_f32 v[44:45], v[168:169], v[44:45]
	v_mfma_f32_16x16x32_bf16 v[16:19], v[72:75], v[64:67], v[16:19]
	v_add_f32_e64 v44, v172, v44
	v_add_f32_e64 v45, v173, v45
	v_pk_add_f32 v[64:65], v[170:171], v[44:45]
	v_mfma_f32_16x16x32_bf16 v[60:63], v[72:75], v[84:87], v[60:63]
	v_add_f32_e64 v64, v166, v64
	v_add_f32_e64 v65, v167, v65
	v_pk_fma_f32 v[162:163], v[162:163], v[180:181], v[64:65]
	v_add_f32_e32 v64, 0, v203
	v_add_f32_e32 v64, v237, v64
	v_add_f32_e32 v64, v246, v64
	v_add_f32_e32 v165, v247, v64
	v_mfma_f32_16x16x32_bf16 v[72:75], v[228:231], v[92:95], v[148:151]
	s_nop 2
	v_add_f32_e64 v148, v190, v164
	v_add_f32_e64 v149, v191, v165
	v_mfma_f32_16x16x32_bf16 v[84:87], v[220:223], v[92:95], v[152:155]
	v_add_f32_e64 v148, v188, v148
	v_add_f32_e64 v149, v189, v149
	v_pk_add_f32 v[148:149], v[186:187], v[148:149]
	v_mfma_f32_16x16x32_bf16 v[44:47], v[220:223], v[52:55], v[216:219]
	v_add_f32_e64 v82, v82, v148
	v_add_f32_e64 v83, v83, v149
	v_pk_add_f32 v[80:81], v[80:81], v[82:83]
	v_mfma_f32_16x16x32_bf16 v[28:31], v[228:231], v[52:55], v[28:31]
	v_add_f32_e64 v80, v184, v80
	v_add_f32_e64 v81, v185, v81
	v_mov_b32_e32 v216, v207
	v_pk_add_f32 v[58:59], v[58:59], v[80:81]
	v_mfma_f32_16x16x32_bf16 v[64:67], v[238:241], v[92:95], v[242:245]
	v_mov_b32_e32 v207, v204
	v_pk_add_f32 v[56:57], v[56:57], v[58:59]
	v_mfma_f32_16x16x32_bf16 v[24:27], v[238:241], v[52:55], v[24:27]
	v_fma_f32 v158, v158, v206, v56
	v_fma_f32 v159, v159, v207, v57
	v_mfma_f32_16x16x32_bf16 v[60:63], v[144:147], v[92:95], v[60:63]
	v_mfma_f32_16x16x32_bf16 v[16:19], v[144:147], v[52:55], v[16:19]
	s_cbranch_scc0 .LBB0_289
	s_waitcnt vmcnt(0)
	v_mov_b32_e32 v20, v163
	s_nop 1
	v_permlane16_swap_b32_e32 v163, v20
	v_add_f32_e32 v20, v163, v20
	s_lshl_b32 s0, s0, 2
	v_mov_b32_e32 v21, v20
	s_add_i32 s0, s0, 0
	s_nop 0
	v_permlane32_swap_b32_e32 v20, v21
	s_add_i32 s0, s0, 0x26800
	v_add_f32_e32 v20, v20, v21
	v_lshl_add_u32 v80, v205, 2, s0
	v_div_scale_f32 v21, s[0:1], v20, v20, 1.0
	v_rcp_f32_e32 v22, v21
	v_cmp_gt_u32_e64 s[4:5], 16, v209
	v_fma_f32 v23, -v21, v22, 1.0
	v_fmac_f32_e32 v22, v23, v22
	v_div_scale_f32 v23, vcc, 1.0, v20, 1.0
	v_mul_f32_e32 v32, v23, v22
	v_fma_f32 v33, -v21, v32, v23
	v_fmac_f32_e32 v32, v33, v22
	v_fma_f32 v21, -v21, v32, v23
	v_div_fmas_f32 v21, v21, v22, v32
	v_div_fixup_f32 v22, v21, v20, 1.0
	v_pk_mul_f32 v[40:41], v[50:51], v[22:23] op_sel_hi:[1,0]
	v_pk_mul_f32 v[42:43], v[48:49], v[22:23] op_sel_hi:[1,0]
	v_mul_f32_e32 v21, v41, v41
	v_mul_f32_e32 v20, v43, v43
	v_fmac_f32_e32 v20, v42, v42
	v_fmac_f32_e32 v21, v40, v40
	v_pk_mul_f32 v[36:37], v[70:71], v[22:23] op_sel_hi:[1,0]
	v_pk_mul_f32 v[38:39], v[68:69], v[22:23] op_sel_hi:[1,0]
	v_add_f32_e32 v20, v20, v21
	v_mul_f32_e32 v21, v39, v39
	v_mul_f32_e32 v23, v37, v37
	v_fmac_f32_e32 v21, v38, v38
	v_fmac_f32_e32 v23, v36, v36
	v_add_f32_e32 v21, v21, v23
	v_pk_mul_f32 v[32:33], v[78:79], v[22:23] op_sel_hi:[1,0]
	v_pk_mul_f32 v[34:35], v[76:77], v[22:23] op_sel_hi:[1,0]
	v_add_f32_e32 v20, v20, v21
	v_mul_f32_e32 v21, v35, v35
	v_mul_f32_e32 v23, v33, v33
	v_fmac_f32_e32 v21, v34, v34
	v_fmac_f32_e32 v23, v32, v32
	v_add_f32_e32 v21, v21, v23
	v_add_f32_e32 v48, v21, v20
	v_pk_mul_f32 v[20:21], v[90:91], v[22:23] op_sel_hi:[1,0]
	v_pk_mul_f32 v[22:23], v[88:89], v[22:23] op_sel_hi:[1,0]
	v_mul_f32_e32 v50, v21, v21
	v_mul_f32_e32 v49, v23, v23
	v_fmac_f32_e32 v49, v22, v22
	v_fmac_f32_e32 v50, v20, v20
	v_add_f32_e32 v49, v49, v50
	v_add_f32_e32 v48, v49, v48
	v_mov_b32_e32 v49, v48
	s_nop 1
	v_permlane16_swap_b32_e32 v48, v49
	v_add_f32_e32 v48, v48, v49
	v_mov_b32_e32 v49, v48
	s_nop 1
	v_permlane32_swap_b32_e32 v48, v49
	s_and_saveexec_b64 s[0:1], s[4:5]
	v_add_f32_e32 v48, v48, v49
	ds_write_b32 v80, v48
	s_or_b64 exec, exec, s[0:1]
	v_mov_b32_e32 v48, v162
	s_nop 1
	v_permlane16_swap_b32_e32 v162, v48
	v_add_f32_e32 v48, v162, v48
	v_mov_b32_e32 v49, v48
	s_nop 1
	v_permlane32_swap_b32_e32 v48, v49
	v_add_f32_e32 v48, v48, v49
	v_div_scale_f32 v49, s[0:1], v48, v48, 1.0
	v_rcp_f32_e32 v50, v49
	s_nop 0
	v_fma_f32 v51, -v49, v50, 1.0
; __device__ __forceinline__ void mixer_attn(const bf16_t* Z, bf16_t* MIX, int b, int r, LAS unsigned char* lds) {
;     ...
;     for (int jq = 0; jq < 4; ++jq) {
;         const float lt = xrow16_sum(lrun[jq]);
;         const float inv = 1.0f / lt; float ss = 0.f;
; #pragma unroll
;         for (int dt = 0; dt < 4; ++dt) { o[jq][dt] *= inv; ss += (o[jq][dt][0] * o[jq][dt][0] + o[jq][dt][1] * o[jq][dt][1]) + (o[jq][dt][2] * o[jq][dt][2] + o[jq][dt][3] * o[jq][dt][3]); }
;         ss = xrow16_sum(ss);
;         if (g == 0) ssbuf[h * 64 + 16 * jq + i] = ss;
;     }
	v_fmac_f32_e32 v50, v51, v50
	v_div_scale_f32 v51, vcc, 1.0, v48, 1.0
	v_mul_f32_e32 v52, v51, v50
	v_fma_f32 v53, -v49, v52, v51
	v_fmac_f32_e32 v52, v53, v50
	v_fma_f32 v49, -v49, v52, v51
	v_div_fmas_f32 v49, v49, v50, v52
	v_div_fixup_f32 v50, v49, v48, 1.0
	v_pk_mul_f32 v[68:69], v[86:87], v[50:51] op_sel_hi:[1,0]
	v_pk_mul_f32 v[70:71], v[84:85], v[50:51] op_sel_hi:[1,0]
	v_mul_f32_e32 v49, v69, v69
	v_mul_f32_e32 v48, v71, v71
	v_fmac_f32_e32 v48, v70, v70
	v_fmac_f32_e32 v49, v68, v68
	v_pk_mul_f32 v[56:57], v[74:75], v[50:51] op_sel_hi:[1,0]
	v_pk_mul_f32 v[58:59], v[72:73], v[50:51] op_sel_hi:[1,0]
	v_add_f32_e32 v48, v48, v49
	v_mul_f32_e32 v49, v59, v59
	v_mul_f32_e32 v51, v57, v57
	v_fmac_f32_e32 v49, v58, v58
	v_fmac_f32_e32 v51, v56, v56
	v_add_f32_e32 v49, v49, v51
	v_pk_mul_f32 v[52:53], v[66:67], v[50:51] op_sel_hi:[1,0]
	v_pk_mul_f32 v[54:55], v[64:65], v[50:51] op_sel_hi:[1,0]
	v_add_f32_e32 v48, v48, v49
	v_mul_f32_e32 v49, v55, v55
	v_mul_f32_e32 v51, v53, v53
	v_fmac_f32_e32 v49, v54, v54
	v_fmac_f32_e32 v51, v52, v52
	v_add_f32_e32 v49, v49, v51
	v_add_f32_e32 v64, v49, v48
	v_pk_mul_f32 v[48:49], v[62:63], v[50:51] op_sel_hi:[1,0]
	v_pk_mul_f32 v[50:51], v[60:61], v[50:51] op_sel_hi:[1,0]
	v_mul_f32_e32 v61, v49, v49
	v_mul_f32_e32 v60, v51, v51
	v_fmac_f32_e32 v60, v50, v50
	v_fmac_f32_e32 v61, v48, v48
	v_add_f32_e32 v60, v60, v61
	v_add_f32_e32 v60, v60, v64
	v_mov_b32_e32 v61, v60
	s_nop 1
	v_permlane16_swap_b32_e32 v60, v61
	v_add_f32_e32 v60, v60, v61
	v_mov_b32_e32 v61, v60
	s_nop 1
	v_permlane32_swap_b32_e32 v60, v61
	s_and_saveexec_b64 s[0:1], s[4:5]
	v_readlane_b32 s74, v255, 9
	v_readlane_b32 s75, v255, 10
	v_add_f32_e32 v60, v60, v61
	ds_write_b32 v80, v60 offset:64
	s_or_b64 exec, exec, s[0:1]
	v_mov_b32_e32 v60, v159
	s_nop 1
	v_permlane16_swap_b32_e32 v159, v60
	v_add_f32_e32 v60, v159, v60
	v_mov_b32_e32 v61, v60
	s_nop 1
	v_permlane32_swap_b32_e32 v60, v61
	v_add_f32_e32 v60, v60, v61
	v_div_scale_f32 v61, s[0:1], v60, v60, 1.0
	v_rcp_f32_e32 v62, v61
	s_nop 0
	v_fma_f32 v63, -v61, v62, 1.0
	v_fmac_f32_e32 v62, v63, v62
	v_div_scale_f32 v63, vcc, 1.0, v60, 1.0
	v_mul_f32_e32 v64, v63, v62
	v_fma_f32 v65, -v61, v64, v63
	v_fmac_f32_e32 v64, v65, v62
	v_fma_f32 v61, -v61, v64, v63
	v_div_fmas_f32 v61, v61, v62, v64
	v_div_fixup_f32 v60, v61, v60, 1.0
	v_pk_mul_f32 v[46:47], v[46:47], v[60:61] op_sel_hi:[1,0]
	v_pk_mul_f32 v[44:45], v[44:45], v[60:61] op_sel_hi:[1,0]
	v_mul_f32_e32 v62, v47, v47
	v_mul_f32_e32 v61, v45, v45
	v_fmac_f32_e32 v61, v44, v44
	v_fmac_f32_e32 v62, v46, v46
	v_add_f32_e32 v61, v61, v62
	v_pk_mul_f32 v[30:31], v[30:31], v[60:61] op_sel_hi:[1,0]
	v_pk_mul_f32 v[28:29], v[28:29], v[60:61] op_sel_hi:[1,0]
	v_mul_f32_e32 v63, v31, v31
	v_mul_f32_e32 v62, v29, v29
	v_fmac_f32_e32 v62, v28, v28
	v_fmac_f32_e32 v63, v30, v30
	v_add_f32_e32 v62, v62, v63
	v_add_f32_e32 v61, v61, v62
	v_pk_mul_f32 v[26:27], v[26:27], v[60:61] op_sel_hi:[1,0]
	v_pk_mul_f32 v[24:25], v[24:25], v[60:61] op_sel_hi:[1,0]
	v_mul_f32_e32 v63, v27, v27
	v_mul_f32_e32 v62, v25, v25
	v_fmac_f32_e32 v62, v24, v24
	v_fmac_f32_e32 v63, v26, v26
	v_add_f32_e32 v62, v62, v63
	v_add_f32_e32 v61, v62, v61
	v_pk_mul_f32 v[18:19], v[18:19], v[60:61] op_sel_hi:[1,0]
	v_pk_mul_f32 v[16:17], v[16:17], v[60:61] op_sel_hi:[1,0]
	v_mul_f32_e32 v62, v19, v19
	v_mul_f32_e32 v60, v17, v17
	v_fmac_f32_e32 v60, v16, v16
	v_fmac_f32_e32 v62, v18, v18
	v_add_f32_e32 v60, v60, v62
	v_add_f32_e32 v60, v60, v61
	v_mov_b32_e32 v61, v60
	s_nop 1
	v_permlane16_swap_b32_e32 v60, v61
	v_add_f32_e32 v60, v60, v61
	v_mov_b32_e32 v61, v60
	s_nop 1
	v_permlane32_swap_b32_e32 v60, v61
	s_and_saveexec_b64 s[0:1], s[4:5]
	v_readlane_b32 s72, v255, 7
	v_readlane_b32 s73, v255, 8
	v_add_f32_e32 v60, v60, v61
	ds_write_b32 v80, v60 offset:128
	s_or_b64 exec, exec, s[0:1]
	v_mov_b32_e32 v60, v158
	s_nop 1
	v_permlane16_swap_b32_e32 v158, v60
	v_add_f32_e32 v60, v158, v60
	v_mov_b32_e32 v61, v60
	s_nop 1
	v_permlane32_swap_b32_e32 v60, v61
	v_add_f32_e32 v60, v60, v61
	v_div_scale_f32 v61, s[0:1], v60, v60, 1.0
	v_rcp_f32_e32 v62, v61
	s_nop 0
	v_fma_f32 v63, -v61, v62, 1.0
	v_fmac_f32_e32 v62, v63, v62
	v_div_scale_f32 v63, vcc, 1.0, v60, 1.0
	v_mul_f32_e32 v64, v63, v62
	v_fma_f32 v65, -v61, v64, v63
	v_fmac_f32_e32 v64, v65, v62
	v_fma_f32 v61, -v61, v64, v63
	v_div_fmas_f32 v61, v61, v62, v64
	v_div_fixup_f32 v60, v61, v60, 1.0
	v_pk_mul_f32 v[14:15], v[14:15], v[60:61] op_sel_hi:[1,0]
	v_pk_mul_f32 v[12:13], v[12:13], v[60:61] op_sel_hi:[1,0]
	v_mul_f32_e32 v62, v15, v15
	v_mul_f32_e32 v61, v13, v13
	v_fmac_f32_e32 v61, v12, v12
	v_fmac_f32_e32 v62, v14, v14
	v_add_f32_e32 v61, v61, v62
	v_pk_mul_f32 v[10:11], v[10:11], v[60:61] op_sel_hi:[1,0]
	v_pk_mul_f32 v[8:9], v[8:9], v[60:61] op_sel_hi:[1,0]
	v_mul_f32_e32 v63, v11, v11
	v_mul_f32_e32 v62, v9, v9
	v_fmac_f32_e32 v62, v8, v8
	v_fmac_f32_e32 v63, v10, v10
	v_add_f32_e32 v62, v62, v63
	v_add_f32_e32 v61, v61, v62
	v_pk_mul_f32 v[6:7], v[6:7], v[60:61] op_sel_hi:[1,0]
	v_pk_mul_f32 v[4:5], v[4:5], v[60:61] op_sel_hi:[1,0]
	v_mul_f32_e32 v63, v7, v7
	v_mul_f32_e32 v62, v5, v5
	v_fmac_f32_e32 v62, v4, v4
	v_fmac_f32_e32 v63, v6, v6
	v_add_f32_e32 v62, v62, v63
	v_add_f32_e32 v61, v62, v61
	v_pk_mul_f32 v[2:3], v[2:3], v[60:61] op_sel_hi:[1,0]
	v_pk_mul_f32 v[0:1], v[0:1], v[60:61] op_sel_hi:[1,0]
	v_mul_f32_e32 v62, v3, v3
	v_mul_f32_e32 v60, v1, v1
	v_fmac_f32_e32 v60, v0, v0
	v_fmac_f32_e32 v62, v2, v2
	v_add_f32_e32 v60, v60, v62
	v_add_f32_e32 v60, v60, v61
	v_mov_b32_e32 v61, v60
	s_nop 1
	v_permlane16_swap_b32_e32 v60, v61
	v_add_f32_e32 v60, v60, v61
	v_mov_b32_e32 v61, v60
	s_nop 1
	v_permlane32_swap_b32_e32 v60, v61
	s_and_saveexec_b64 s[0:1], s[4:5]
	v_readlane_b32 s76, v255, 19
	v_add_f32_e32 v60, v60, v61
	ds_write_b32 v80, v60 offset:192
	s_or_b64 exec, exec, s[0:1]
	v_lshl_add_u32 v60, v205, 2, 0
	v_add_u32_e32 v72, 0x26800, v60
	s_waitcnt lgkmcnt(0)
	s_barrier
; __device__ __forceinline__ unsigned cvt_pk_bf16(float lo, float hi) { unsigned r; asm volatile("v_cvt_pk_bf16_f32 %0, %1, %2" : "=v"(r) : "v"(lo), "v"(hi)); return r; }
; __device__ __forceinline__ void mixer_attn(const bf16_t* Z, bf16_t* MIX, int b, int r, LAS unsigned char* lds) {
;     ...
;     __syncthreads();
;     bf16_t* mo = MIX + ((size_t)b * SEQ + r * 64) * DM + h * 64 + 4 * g;
; #pragma unroll
;     for (int jq = 0; jq < 4; ++jq) {
;         float tot = 0.f;
; #pragma unroll
;         for (int hh = 0; hh < 8; ++hh) tot += ssbuf[hh * 64 + 16 * jq + i];
;         const float rinv = __builtin_amdgcn_rsqf(tot * (1.0f / 512.0f) + EPS);
; #pragma unroll
;         for (int dt = 0; dt < 4; ++dt) { const f32x4 v = o[jq][dt] * rinv;
;             *(unsigned long long*)(mo + (size_t)(16 * jq + i) * DM + 16 * dt) = (unsigned long long)pg8::cvt_pk_bf16(v[0], v[1]) | ((unsigned long long)pg8::cvt_pk_bf16(v[2], v[3]) << 32); }
;     }
;     __syncthreads();
	ds_read2st64_b32 v[60:61], v72 offset1:1
	ds_read2st64_b32 v[62:63], v72 offset0:2 offset1:3
	ds_read2st64_b32 v[64:65], v72 offset0:4 offset1:5
	ds_read2st64_b32 v[66:67], v72 offset0:6 offset1:7
	s_lshl_b64 s[0:1], s[96:97], 11
	s_add_u32 s0, s74, s0
	s_addc_u32 s1, s75, s1
	s_waitcnt lgkmcnt(3)
	v_add_f32_e32 v60, 0, v60
	v_add_f32_e32 v60, v60, v61
	s_waitcnt lgkmcnt(2)
	v_add_f32_e32 v60, v60, v62
	v_add_f32_e32 v60, v60, v63
	s_waitcnt lgkmcnt(1)
	v_add_f32_e32 v60, v60, v64
	v_add_f32_e32 v60, v60, v65
	s_waitcnt lgkmcnt(0)
	v_add_f32_e32 v60, v60, v66
	v_add_f32_e32 v60, v60, v67
	v_fmamk_f32 v60, v60, 0x3b000000, v233
	v_rsq_f32_e32 v60, v60
	s_add_u32 s0, s0, s80
	s_addc_u32 s1, s1, s81
	v_lshlrev_b32_e32 v192, 1, v208
	v_lshl_add_u64 v[62:63], s[0:1], 0, v[192:193]
	v_lshlrev_b32_e32 v192, 11, v205
	v_lshl_add_u64 v[62:63], v[62:63], 0, v[192:193]
	v_pk_mul_f32 v[42:43], v[42:43], v[60:61] op_sel_hi:[1,0]
	v_pk_mul_f32 v[38:39], v[38:39], v[60:61] op_sel_hi:[1,0]
	v_pk_mul_f32 v[34:35], v[34:35], v[60:61] op_sel_hi:[1,0]
	v_pk_mul_f32 v[20:21], v[20:21], v[60:61] op_sel_hi:[1,0]
	v_pk_mul_f32 v[22:23], v[22:23], v[60:61] op_sel_hi:[1,0]
	v_pk_mul_f32 v[40:41], v[40:41], v[60:61] op_sel_hi:[1,0]
	v_cvt_pk_bf16_f32 v42, v42, v43
	v_pk_mul_f32 v[36:37], v[36:37], v[60:61] op_sel_hi:[1,0]
	v_cvt_pk_bf16_f32 v43, v40, v41
	global_store_dwordx2 v[62:63], v[42:43], off
	v_cvt_pk_bf16_f32 v38, v38, v39
	v_cvt_pk_bf16_f32 v39, v36, v37
	global_store_dwordx2 v[62:63], v[38:39], off offset:32
	v_pk_mul_f32 v[32:33], v[32:33], v[60:61] op_sel_hi:[1,0]
	v_cvt_pk_bf16_f32 v34, v34, v35
	v_add_u32_e32 v36, 64, v72
	v_cvt_pk_bf16_f32 v35, v32, v33
	global_store_dwordx2 v[62:63], v[34:35], off offset:64
	v_cvt_pk_bf16_f32 v22, v22, v23
	v_cvt_pk_bf16_f32 v23, v20, v21
	ds_read2_b32 v[20:21], v72 offset0:16 offset1:80
	ds_read2_b32 v[32:33], v72 offset0:144 offset1:208
	ds_read2st64_b32 v[34:35], v36 offset0:4 offset1:5
	global_store_dwordx2 v[62:63], v[22:23], off offset:96
	s_mov_b32 s0, 0x8000
	s_waitcnt lgkmcnt(2)
	v_add_f32_e32 v20, 0, v20
	v_add_f32_e32 v37, v20, v21
	ds_read2st64_b32 v[20:21], v36 offset0:6 offset1:7
	s_waitcnt lgkmcnt(2)
	v_add_f32_e32 v32, v37, v32
	v_add_f32_e32 v32, v32, v33
	s_waitcnt lgkmcnt(1)
	v_add_f32_e32 v32, v32, v34
	v_add_f32_e32 v32, v32, v35
	s_waitcnt lgkmcnt(0)
	v_add_f32_e32 v20, v32, v20
	v_add_f32_e32 v20, v20, v21
	v_fmamk_f32 v20, v20, 0x3b000000, v233
	v_rsq_f32_e32 v20, v20
	v_add_u32_e32 v38, 0x80, v72
	v_readlane_b32 s4, v255, 32
	v_readlane_b32 s5, v255, 33
	v_pk_mul_f32 v[22:23], v[68:69], v[20:21] op_sel_hi:[1,0]
	v_pk_mul_f32 v[32:33], v[70:71], v[20:21] op_sel_hi:[1,0]
	v_pk_mul_f32 v[34:35], v[58:59], v[20:21] op_sel_hi:[1,0]
	v_cvt_pk_bf16_f32 v32, v32, v33
	v_cvt_pk_bf16_f32 v33, v22, v23
	v_add_co_u32_e32 v22, vcc, s0, v62
	s_mov_b32 s0, 0x10000
	s_nop 0
	v_addc_co_u32_e32 v23, vcc, 0, v63, vcc
	global_store_dwordx2 v[22:23], v[32:33], off
	v_pk_mul_f32 v[32:33], v[56:57], v[20:21] op_sel_hi:[1,0]
	v_cvt_pk_bf16_f32 v34, v34, v35
	s_mov_b32 s2, 0
	v_cvt_pk_bf16_f32 v35, v32, v33
	global_store_dwordx2 v[22:23], v[34:35], off offset:32
	v_pk_mul_f32 v[32:33], v[52:53], v[20:21] op_sel_hi:[1,0]
	v_pk_mul_f32 v[34:35], v[54:55], v[20:21] op_sel_hi:[1,0]
	s_movk_i32 s10, 0x1000
	v_cvt_pk_bf16_f32 v34, v34, v35
	v_cvt_pk_bf16_f32 v35, v32, v33
	v_pk_mul_f32 v[32:33], v[48:49], v[20:21] op_sel_hi:[1,0]
	v_pk_mul_f32 v[20:21], v[50:51], v[20:21] op_sel_hi:[1,0]
	global_store_dwordx2 v[22:23], v[34:35], off offset:64
	v_cvt_pk_bf16_f32 v20, v20, v21
	v_cvt_pk_bf16_f32 v21, v32, v33
	ds_read2_b32 v[32:33], v72 offset0:32 offset1:96
	ds_read2_b32 v[34:35], v72 offset0:160 offset1:224
	ds_read2st64_b32 v[36:37], v38 offset0:4 offset1:5
	global_store_dwordx2 v[22:23], v[20:21], off offset:96
	s_waitcnt lgkmcnt(2)
	v_add_f32_e32 v32, 0, v32
	v_add_f32_e32 v39, v32, v33
	ds_read2st64_b32 v[32:33], v38 offset0:6 offset1:7
	s_waitcnt lgkmcnt(2)
	v_add_f32_e32 v34, v39, v34
	v_add_f32_e32 v34, v34, v35
	s_waitcnt lgkmcnt(1)
	v_add_f32_e32 v34, v34, v36
	v_add_f32_e32 v34, v34, v37
	s_waitcnt lgkmcnt(0)
	v_add_f32_e32 v32, v34, v32
	v_add_f32_e32 v32, v32, v33
	v_fmamk_f32 v32, v32, 0x3b000000, v233
	v_rsq_f32_e32 v32, v32
	s_nop 0
	v_pk_mul_f32 v[20:21], v[46:47], v[32:33] op_sel_hi:[1,0]
	v_pk_mul_f32 v[22:23], v[44:45], v[32:33] op_sel_hi:[1,0]
	v_pk_mul_f32 v[28:29], v[28:29], v[32:33] op_sel_hi:[1,0]
	v_cvt_pk_bf16_f32 v22, v22, v23
	v_cvt_pk_bf16_f32 v23, v20, v21
	v_add_co_u32_e32 v20, vcc, s0, v62
	v_pk_mul_f32 v[24:25], v[24:25], v[32:33] op_sel_hi:[1,0]
	s_nop 0
	v_addc_co_u32_e32 v21, vcc, 0, v63, vcc
	global_store_dwordx2 v[20:21], v[22:23], off
	v_pk_mul_f32 v[22:23], v[30:31], v[32:33] op_sel_hi:[1,0]
	v_pk_mul_f32 v[18:19], v[18:19], v[32:33] op_sel_hi:[1,0]
	v_pk_mul_f32 v[16:17], v[16:17], v[32:33] op_sel_hi:[1,0]
	v_cvt_pk_bf16_f32 v28, v28, v29
	v_cvt_pk_bf16_f32 v29, v22, v23
	global_store_dwordx2 v[20:21], v[28:29], off offset:32
	v_pk_mul_f32 v[22:23], v[26:27], v[32:33] op_sel_hi:[1,0]
	v_cvt_pk_bf16_f32 v24, v24, v25
	v_add_u32_e32 v26, 0xc0, v72
	v_cvt_pk_bf16_f32 v25, v22, v23
	global_store_dwordx2 v[20:21], v[24:25], off offset:64
	v_cvt_pk_bf16_f32 v16, v16, v17
	v_cvt_pk_bf16_f32 v17, v18, v19
	ds_read2_b32 v[18:19], v72 offset0:48 offset1:112
	ds_read2_b32 v[22:23], v72 offset0:176 offset1:240
	ds_read2st64_b32 v[24:25], v26 offset0:4 offset1:5
	global_store_dwordx2 v[20:21], v[16:17], off offset:96
	s_mov_b64 s[0:1], 0x1000
	s_waitcnt lgkmcnt(2)
	v_add_f32_e32 v18, 0, v18
	v_add_f32_e32 v27, v18, v19
	ds_read2st64_b32 v[18:19], v26 offset0:6 offset1:7
	s_waitcnt lgkmcnt(2)
	v_add_f32_e32 v22, v27, v22
	v_add_f32_e32 v22, v22, v23
	s_waitcnt lgkmcnt(1)
	v_add_f32_e32 v22, v22, v24
	v_add_f32_e32 v22, v22, v25
	s_waitcnt lgkmcnt(0)
	v_add_f32_e32 v18, v22, v18
	v_add_f32_e32 v18, v18, v19
	v_fmamk_f32 v18, v18, 0x3b000000, v233
	v_rsq_f32_e32 v18, v18
	v_mov_b32_e32 v24, v232
	v_pk_mul_f32 v[14:15], v[14:15], v[18:19] op_sel_hi:[1,0]
	v_pk_mul_f32 v[12:13], v[12:13], v[18:19] op_sel_hi:[1,0]
	v_pk_mul_f32 v[8:9], v[8:9], v[18:19] op_sel_hi:[1,0]
	v_cvt_pk_bf16_f32 v12, v12, v13
	v_cvt_pk_bf16_f32 v13, v14, v15
	v_add_co_u32_e32 v14, vcc, s3, v62
	v_pk_mul_f32 v[4:5], v[4:5], v[18:19] op_sel_hi:[1,0]
	s_nop 0
	v_addc_co_u32_e32 v15, vcc, 0, v63, vcc
	v_pk_mul_f32 v[0:1], v[0:1], v[18:19] op_sel_hi:[1,0]
	global_store_dwordx2 v[14:15], v[12:13], off
	v_pk_mul_f32 v[10:11], v[10:11], v[18:19] op_sel_hi:[1,0]
	v_cvt_pk_bf16_f32 v8, v8, v9
	v_pk_mul_f32 v[6:7], v[6:7], v[18:19] op_sel_hi:[1,0]
	v_cvt_pk_bf16_f32 v9, v10, v11
	global_store_dwordx2 v[14:15], v[8:9], off offset:32
	v_cvt_pk_bf16_f32 v4, v4, v5
	v_cvt_pk_bf16_f32 v5, v6, v7
	global_store_dwordx2 v[14:15], v[4:5], off offset:64
	v_cvt_pk_bf16_f32 v0, v0, v1
	v_pk_mul_f32 v[2:3], v[2:3], v[18:19] op_sel_hi:[1,0]
	s_nop 0
	v_cvt_pk_bf16_f32 v1, v2, v3
	global_store_dwordx2 v[14:15], v[0:1], off offset:96
	s_barrier
; __device__ __forceinline__ void mixer_conv(const bf16_t* Z, bf16_t* MIX, const float* convw, int b, int r) {
;     ...
;     float w[3][8];
; #pragma unroll
;     for (int k = 0; k < 3; ++k) { const f32x4 a = *(const f32x4*)(convw + k * 512 + ch), c = *(const f32x4*)(convw + k * 512 + ch + 4);
; #pragma unroll
;         for (int e = 0; e < 4; ++e) { w[k][e] = a[e]; w[k][4 + e] = c[e]; } }
;     ...
;         for (int o = 1; o < 64; o <<= 1)
; #pragma unroll
;             for (int j = 0; j < 4; ++j) ss[j] += __shfl_xor(ss[j], o);
	s_nop 0
	v_lshlrev_b32_e32 v0, 3, v24
	v_and_b32_e32 v25, 0x1f8, v0
	v_lshlrev_b32_e32 v192, 2, v25
	v_lshl_add_u64 v[12:13], s[4:5], 0, v[192:193]
	v_lshl_add_u64 v[4:5], v[12:13], 0, s[0:1]
	s_movk_i32 s0, 0x1000
	v_add_co_u32_e32 v12, vcc, s0, v12
	global_load_dwordx4 v[0:3], v192, s[4:5] offset:16
	s_nop 0
	v_addc_co_u32_e32 v13, vcc, 0, v13, vcc
	global_load_dwordx4 v[4:7], v[4:5], off offset:16
	s_nop 0
	global_load_dwordx4 v[8:11], v192, s[4:5]
	s_nop 0
	global_load_dwordx4 v[12:15], v[12:13], off
	s_nop 0
	global_load_dwordx4 v[16:19], v192, s[4:5] offset:2064
	global_load_dwordx4 v[20:23], v192, s[4:5] offset:2048
	v_ashrrev_i32_e32 v24, 3, v24
	v_and_b32_e32 v24, -8, v24
	v_readlane_b32 s1, v255, 34
	v_lshlrev_b32_e32 v192, 1, v25
	v_xor_b32_e32 v25, 1, v236
	v_add_u32_e32 v150, s1, v24
	v_and_b32_e32 v24, 64, v236
	v_add_u32_e32 v24, 64, v24
	v_cmp_lt_i32_e32 vcc, v25, v24
	v_lshl_add_u64 v[80:81], s[72:73], 0, v[192:193]
	v_cmp_gt_u32_e64 s[4:5], s0, v150
	v_cndmask_b32_e32 v25, v236, v25, vcc
	v_lshlrev_b32_e32 v151, 2, v25
	v_xor_b32_e32 v25, 2, v236
	v_cmp_lt_i32_e32 vcc, v25, v24
	v_lshl_add_u64 v[130:131], s[74:75], 0, v[192:193]
	s_mov_b64 s[0:1], -1
	v_cndmask_b32_e32 v25, v236, v25, vcc
	v_lshlrev_b32_e32 v152, 2, v25
	v_xor_b32_e32 v25, 4, v236
	v_cmp_lt_i32_e32 vcc, v25, v24
	s_waitcnt vmcnt(5)
	v_mov_b32_e32 v82, v2
	v_cndmask_b32_e32 v25, v236, v25, vcc
	v_lshlrev_b32_e32 v153, 2, v25
	v_xor_b32_e32 v25, 8, v236
	v_cmp_lt_i32_e32 vcc, v25, v24
	s_waitcnt vmcnt(4)
	v_mov_b32_e32 v83, v6
	v_mov_b32_e32 v84, v3
	v_cndmask_b32_e32 v25, v236, v25, vcc
	v_lshlrev_b32_e32 v154, 2, v25
	v_xor_b32_e32 v25, 16, v236
	v_cmp_lt_i32_e32 vcc, v25, v24
	v_mov_b32_e32 v85, v7
	v_mov_b32_e32 v86, v0
	v_cndmask_b32_e32 v25, v236, v25, vcc
	v_lshlrev_b32_e32 v155, 2, v25
	v_xor_b32_e32 v25, 32, v236
	v_cmp_lt_i32_e32 vcc, v25, v24
	v_mov_b32_e32 v87, v4
	v_mov_b32_e32 v88, v1
	v_cndmask_b32_e32 v24, v236, v25, vcc
	v_lshlrev_b32_e32 v156, 2, v24
	v_mov_b32_e32 v89, v5
	s_waitcnt vmcnt(3)
	v_mov_b32_e32 v90, v10
	s_waitcnt vmcnt(2)
	v_mov_b32_e32 v91, v14
	v_mov_b32_e32 v92, v11
	v_mov_b32_e32 v93, v15
	v_mov_b32_e32 v94, v8
	v_mov_b32_e32 v95, v12
	v_mov_b32_e32 v96, v9
	v_mov_b32_e32 v97, v13
	v_mov_b32_e32 v98, v2
	s_waitcnt vmcnt(1)
	v_mov_b32_e32 v99, v18
	v_mov_b32_e32 v100, v3
	v_mov_b32_e32 v101, v19
	v_mov_b32_e32 v102, v0
	v_mov_b32_e32 v103, v16
	v_mov_b32_e32 v104, v1
	v_mov_b32_e32 v105, v17
	v_mov_b32_e32 v106, v10
	s_waitcnt vmcnt(0)
	v_mov_b32_e32 v107, v22
	v_mov_b32_e32 v108, v11
	v_mov_b32_e32 v109, v23
	v_mov_b32_e32 v110, v8
	v_mov_b32_e32 v111, v20
	v_mov_b32_e32 v112, v9
	v_mov_b32_e32 v113, v21
	v_mov_b32_e32 v114, v18
	v_mov_b32_e32 v115, v6
	v_mov_b32_e32 v116, v19
	v_mov_b32_e32 v117, v7
	v_mov_b32_e32 v118, v16
	v_mov_b32_e32 v119, v4
	v_mov_b32_e32 v120, v17
	v_mov_b32_e32 v121, v5
	v_mov_b32_e32 v122, v22
	v_mov_b32_e32 v123, v14
	v_mov_b32_e32 v124, v23
	v_mov_b32_e32 v125, v15
	v_mov_b32_e32 v126, v20
	v_mov_b32_e32 v127, v12
	v_mov_b32_e32 v128, v21
	v_mov_b32_e32 v129, v13
	s_branch .LBB0_300

; #define LAS __attribute__((address_space(3)))
; __device__ __forceinline__ float fast_sigmoid(float x) { return __builtin_amdgcn_rcpf(1.0f + __expf(-x)); }
;     __device__ __forceinline__ void operator()(const f32x4 (&acc)[2][2][4][2], const pg8::Unit& u, int wr, int wc, int fr_, int fq_, LAS const unsigned char* xl) const {
;     ...
;         if (MODE == 0 || MODE == 1 || MODE == 4) {
; #pragma unroll
;             for (int ai = 0; ai < 2; ++ai)
; #pragma unroll
;                 for (int m = 0; m < 4; ++m) { const f32x4 pv = *(LAS const f32x4*)(xl + (ai * 128 + wr * 64 + m * 16 + fr) * 64 + fq * 16); rv[ai][m] = (pv[0] + pv[1]) + (pv[2] + pv[3]); }
; #pragma unroll
;             for (int ai = 0; ai < 2; ++ai)
; #pragma unroll
;                 for (int m = 0; m < 4; ++m) rv[ai][m] = __builtin_amdgcn_rsqf(xrow16_sum(rv[ai][m]) * (1.0f / 1024.0f) + EPS);
;         }
;         if (MODE == 0 || MODE == 1 || MODE == 2) {
; #pragma unroll
;             for (int ai = 0; ai < 2; ++ai)
; #pragma unroll
;                 for (int m = 0; m < 4; ++m) {
;                     const int row = row0 + ai * 128 + m * 16;
;                     const float rinv = (MODE == 2) ? 1.f : rv[ai][m];
;                     if (MODE == 0 || MODE == 2) {
;                         bf16_t* rowp = O + (size_t)row * ldc + u.pn * 256 + wc * 32 + 8 * fq;
; #pragma unroll
;                         for (int bj = 0; bj < 2; ++bj) { const f32x4 v0 = acc[ai][bj][m][0] * rinv, v1 = acc[ai][bj][m][1] * rinv;
;                             u32x4 w; w.x = pg8::cvt_pk_bf16(v0[0], v0[1]); w.y = pg8::cvt_pk_bf16(v0[2], v0[3]); w.z = pg8::cvt_pk_bf16(v1[0], v1[1]); w.w = pg8::cvt_pk_bf16(v1[2], v1[3]);
;                             *(u32x4*)(rowp + bj * 128) = w; }
;                     } else {
;                         bf16_t* rowp = O + (size_t)row * ldc + u.pn * 128 + wc * 32 + 8 * fq;
;                         float a[8];
; #pragma unroll
;                         for (int n = 0; n < 2; ++n)
; #pragma unroll
;                             for (int j = 0; j < 4; ++j) { const float g = acc[ai][0][m][n][j] * rinv, up = acc[ai][1][m][n][j] * rinv; a[4 * n + j] = g * fast_sigmoid(g) * up; }
;                         u32x4 w; w.x = pg8::cvt_pk_bf16(a[0], a[1]); w.y = pg8::cvt_pk_bf16(a[2], a[3]); w.z = pg8::cvt_pk_bf16(a[4], a[5]); w.w = pg8::cvt_pk_bf16(a[6], a[7]);
;                         *(u32x4*)rowp = w;
.LBB0_425:
	s_and_b64 vcc, exec, s[6:7]
	v_add_u32_e32 v135, s48, v237
	v_lshlrev_b32_e32 v128, 4, v238
	v_lshlrev_b32_e32 v129, 6, v135
	s_mov_b32 s1, 0x20000
	v_add3_u32 v132, s1, v128, v129
	ds_read_b128 v[152:155], v132
	ds_read_b128 v[156:159], v132 offset:1024
	ds_read_b128 v[160:163], v132 offset:2048
	ds_read_b128 v[164:167], v132 offset:3072
	ds_read_b128 v[168:171], v132 offset:8192
	ds_read_b128 v[172:175], v132 offset:9216
	ds_read_b128 v[176:179], v132 offset:10240
	ds_read_b128 v[180:183], v132 offset:11264
	v_lshl_add_u32 v129, s0, 8, v135
	v_mov_b64_e32 v[130:131], s[72:73]
	s_lshl_b32 s0, s2, 7
	v_mad_i64_i32 v[148:149], s[26:27], v129, s83, v[130:131]
	s_ashr_i32 s1, s0, 31
	s_lshl_b64 s[0:1], s[0:1], 1
	v_lshlrev_b32_e32 v146, 3, v238
	v_ashrrev_i32_e32 v147, 31, v146
	v_lshl_add_u64 v[148:149], v[148:149], 0, s[0:1]
	v_lshl_add_u64 v[148:149], v[148:149], 0, s[86:87]
	v_lshlrev_b64 v[146:147], 1, v[146:147]
	v_lshl_add_u64 v[148:149], v[148:149], 0, v[146:147]
	s_mov_b32 s100, 0x18000
	s_mov_b32 s101, 0
	s_mov_b32 s0, 0x78000
	s_mov_b32 s1, 0
	s_waitcnt lgkmcnt(0)
	v_add_f32_e32 v152, v152, v153
	v_add_f32_e32 v154, v154, v155
	v_add_f32_e32 v156, v156, v157
	v_add_f32_e32 v158, v158, v159
	v_add_f32_e32 v160, v160, v161
	v_add_f32_e32 v162, v162, v163
	v_add_f32_e32 v164, v164, v165
	v_add_f32_e32 v166, v166, v167
	v_add_f32_e32 v168, v168, v169
	v_add_f32_e32 v170, v170, v171
	v_add_f32_e32 v172, v172, v173
	v_add_f32_e32 v174, v174, v175
	v_add_f32_e32 v176, v176, v177
	v_add_f32_e32 v178, v178, v179
	v_add_f32_e32 v180, v180, v181
	v_add_f32_e32 v182, v182, v183
	v_add_f32_e32 v184, v152, v154
	v_add_f32_e32 v185, v156, v158
	v_add_f32_e32 v186, v160, v162
	v_add_f32_e32 v187, v164, v166
	v_add_f32_e32 v188, v168, v170
	v_add_f32_e32 v189, v172, v174
	v_add_f32_e32 v190, v176, v178
	v_add_f32_e32 v191, v180, v182
	v_mov_b32_e32 v152, v184
	v_mov_b32_e32 v153, v185
	v_mov_b32_e32 v154, v186
	v_mov_b32_e32 v155, v187
	v_mov_b32_e32 v156, v188
	v_mov_b32_e32 v157, v189
	v_mov_b32_e32 v158, v190
	v_mov_b32_e32 v159, v191
	v_permlane16_swap_b32_e32 v184, v152
	v_permlane16_swap_b32_e32 v185, v153
	v_permlane16_swap_b32_e32 v186, v154
	v_permlane16_swap_b32_e32 v187, v155
	v_permlane16_swap_b32_e32 v188, v156
	v_permlane16_swap_b32_e32 v189, v157
	v_permlane16_swap_b32_e32 v190, v158
	v_permlane16_swap_b32_e32 v191, v159
	v_add_f32_e32 v184, v184, v152
	v_add_f32_e32 v185, v185, v153
	v_add_f32_e32 v186, v186, v154
	v_add_f32_e32 v187, v187, v155
	v_add_f32_e32 v188, v188, v156
	v_add_f32_e32 v189, v189, v157
	v_add_f32_e32 v190, v190, v158
	v_add_f32_e32 v191, v191, v159
	v_mov_b32_e32 v152, v184
	v_mov_b32_e32 v153, v185
	v_mov_b32_e32 v154, v186
	v_mov_b32_e32 v155, v187
	v_mov_b32_e32 v156, v188
	v_mov_b32_e32 v157, v189
	v_mov_b32_e32 v158, v190
	v_mov_b32_e32 v159, v191
	v_permlane32_swap_b32_e32 v184, v152
	v_permlane32_swap_b32_e32 v185, v153
	v_permlane32_swap_b32_e32 v186, v154
	v_permlane32_swap_b32_e32 v187, v155
	v_permlane32_swap_b32_e32 v188, v156
	v_permlane32_swap_b32_e32 v189, v157
	v_permlane32_swap_b32_e32 v190, v158
	v_permlane32_swap_b32_e32 v191, v159
	v_add_f32_e32 v184, v184, v152
	v_add_f32_e32 v185, v185, v153
	v_add_f32_e32 v186, v186, v154
	v_add_f32_e32 v187, v187, v155
	v_add_f32_e32 v188, v188, v156
	v_add_f32_e32 v189, v189, v157
	v_add_f32_e32 v190, v190, v158
	v_add_f32_e32 v191, v191, v159
	v_fmamk_f32 v184, v184, 0x3a800000, v233
	v_fmamk_f32 v185, v185, 0x3a800000, v233
	v_fmamk_f32 v186, v186, 0x3a800000, v233
	v_fmamk_f32 v187, v187, 0x3a800000, v233
	v_fmamk_f32 v188, v188, 0x3a800000, v233
	v_fmamk_f32 v189, v189, 0x3a800000, v233
	v_fmamk_f32 v190, v190, 0x3a800000, v233
	v_fmamk_f32 v191, v191, 0x3a800000, v233
	v_rsq_f32_e32 v152, v184
	v_rsq_f32_e32 v156, v185
	v_rsq_f32_e32 v160, v186
	v_rsq_f32_e32 v164, v187
	v_rsq_f32_e32 v168, v188
	v_rsq_f32_e32 v172, v189
	v_rsq_f32_e32 v176, v190
	v_rsq_f32_e32 v180, v191
	v_mul_f32_e32 v152, 0xbfb8aa3b, v152
	v_mul_f32_e32 v156, 0xbfb8aa3b, v156
	v_mul_f32_e32 v160, 0xbfb8aa3b, v160
	v_mul_f32_e32 v164, 0xbfb8aa3b, v164
	v_mul_f32_e32 v168, 0xbfb8aa3b, v168
	v_mul_f32_e32 v172, 0xbfb8aa3b, v172
	v_mul_f32_e32 v176, 0xbfb8aa3b, v176
	v_mul_f32_e32 v180, 0xbfb8aa3b, v180
	v_pk_mul_f32 v[124:125], v[120:121], v[124:125]
	v_pk_mul_f32 v[126:127], v[122:123], v[126:127]
	v_pk_mul_f32 v[116:117], v[112:113], v[116:117]
	v_pk_mul_f32 v[118:119], v[114:115], v[118:119]
	v_pk_mul_f32 v[120:121], v[120:121], v[152:153] op_sel_hi:[1,0]
	v_pk_mul_f32 v[122:123], v[122:123], v[152:153] op_sel_hi:[1,0]
	v_pk_mul_f32 v[112:113], v[112:113], v[152:153] op_sel_hi:[1,0]
	v_pk_mul_f32 v[114:115], v[114:115], v[152:153] op_sel_hi:[1,0]
	v_exp_f32_e32 v120, v120
	v_exp_f32_e32 v121, v121
	v_exp_f32_e32 v122, v122
	v_exp_f32_e32 v123, v123
	v_exp_f32_e32 v112, v112
	v_exp_f32_e32 v113, v113
	v_exp_f32_e32 v114, v114
	v_exp_f32_e32 v115, v115
	v_fma_f32 v120, v120, v184, v184
	v_fma_f32 v121, v121, v184, v184
	v_fma_f32 v122, v122, v184, v184
	v_fma_f32 v123, v123, v184, v184
	v_fma_f32 v112, v112, v184, v184
	v_fma_f32 v113, v113, v184, v184
	v_fma_f32 v114, v114, v184, v184
	v_fma_f32 v115, v115, v184, v184
	v_rcp_f32_e32 v120, v120
	v_rcp_f32_e32 v121, v121
	v_rcp_f32_e32 v122, v122
	v_rcp_f32_e32 v123, v123
	v_rcp_f32_e32 v112, v112
	v_rcp_f32_e32 v113, v113
	v_rcp_f32_e32 v114, v114
	v_rcp_f32_e32 v115, v115
	v_lshl_add_u64 v[150:151], v[148:149], 0, s[100:101]
	v_pk_mul_f32 v[124:125], v[124:125], v[120:121]
	v_pk_mul_f32 v[126:127], v[126:127], v[122:123]
	v_pk_mul_f32 v[116:117], v[116:117], v[112:113]
	v_pk_mul_f32 v[118:119], v[118:119], v[114:115]
; __device__ __forceinline__ unsigned cvt_pk_bf16(float lo, float hi) { unsigned r; asm volatile("v_cvt_pk_bf16_f32 %0, %1, %2" : "=v"(r) : "v"(lo), "v"(hi)); return r; }
; __device__ __forceinline__ float fast_sigmoid(float x) { return __builtin_amdgcn_rcpf(1.0f + __expf(-x)); }
;     __device__ __forceinline__ void operator()(const f32x4 (&acc)[2][2][4][2], const pg8::Unit& u, int wr, int wc, int fr_, int fq_, LAS const unsigned char* xl) const {
;     ...
;                     } else {
;                         bf16_t* rowp = O + (size_t)row * ldc + u.pn * 128 + wc * 32 + 8 * fq;
;                         float a[8];
; #pragma unroll
;                         for (int n = 0; n < 2; ++n)
; #pragma unroll
;                             for (int j = 0; j < 4; ++j) { const float g = acc[ai][0][m][n][j] * rinv, up = acc[ai][1][m][n][j] * rinv; a[4 * n + j] = g * fast_sigmoid(g) * up; }
;                         u32x4 w; w.x = pg8::cvt_pk_bf16(a[0], a[1]); w.y = pg8::cvt_pk_bf16(a[2], a[3]); w.z = pg8::cvt_pk_bf16(a[4], a[5]); w.w = pg8::cvt_pk_bf16(a[6], a[7]);
;                         *(u32x4*)rowp = w;
	s_nop 0
	v_cvt_pk_bf16_f32 v136, v124, v125
	v_cvt_pk_bf16_f32 v137, v126, v127
	v_cvt_pk_bf16_f32 v138, v116, v117
	v_cvt_pk_bf16_f32 v139, v118, v119
	global_store_dwordx4 v[148:149], v[136:139], off
	v_pk_mul_f32 v[108:109], v[104:105], v[108:109]
	v_pk_mul_f32 v[110:111], v[106:107], v[110:111]
	v_pk_mul_f32 v[100:101], v[96:97], v[100:101]
	v_pk_mul_f32 v[102:103], v[98:99], v[102:103]
	v_pk_mul_f32 v[104:105], v[104:105], v[156:157] op_sel_hi:[1,0]
	v_pk_mul_f32 v[106:107], v[106:107], v[156:157] op_sel_hi:[1,0]
	v_pk_mul_f32 v[96:97], v[96:97], v[156:157] op_sel_hi:[1,0]
	v_pk_mul_f32 v[98:99], v[98:99], v[156:157] op_sel_hi:[1,0]
	v_exp_f32_e32 v104, v104
	v_exp_f32_e32 v105, v105
	v_exp_f32_e32 v106, v106
	v_exp_f32_e32 v107, v107
	v_exp_f32_e32 v96, v96
	v_exp_f32_e32 v97, v97
	v_exp_f32_e32 v98, v98
	v_exp_f32_e32 v99, v99
	v_fma_f32 v104, v104, v185, v185
	v_fma_f32 v105, v105, v185, v185
	v_fma_f32 v106, v106, v185, v185
	v_fma_f32 v107, v107, v185, v185
	v_fma_f32 v96, v96, v185, v185
	v_fma_f32 v97, v97, v185, v185
	v_fma_f32 v98, v98, v185, v185
	v_fma_f32 v99, v99, v185, v185
	v_rcp_f32_e32 v104, v104
	v_rcp_f32_e32 v105, v105
	v_rcp_f32_e32 v106, v106
	v_rcp_f32_e32 v107, v107
	v_rcp_f32_e32 v96, v96
	v_rcp_f32_e32 v97, v97
	v_rcp_f32_e32 v98, v98
	v_rcp_f32_e32 v99, v99
	v_lshl_add_u64 v[148:149], v[150:151], 0, s[100:101]
	v_pk_mul_f32 v[108:109], v[108:109], v[104:105]
	v_pk_mul_f32 v[110:111], v[110:111], v[106:107]
	v_pk_mul_f32 v[100:101], v[100:101], v[96:97]
	v_pk_mul_f32 v[102:103], v[102:103], v[98:99]
	s_nop 0
	v_cvt_pk_bf16_f32 v140, v108, v109
	v_cvt_pk_bf16_f32 v141, v110, v111
	v_cvt_pk_bf16_f32 v142, v100, v101
	v_cvt_pk_bf16_f32 v143, v102, v103
	global_store_dwordx4 v[150:151], v[140:143], off
	v_pk_mul_f32 v[92:93], v[88:89], v[92:93]
	v_pk_mul_f32 v[94:95], v[90:91], v[94:95]
	v_pk_mul_f32 v[84:85], v[80:81], v[84:85]
	v_pk_mul_f32 v[86:87], v[82:83], v[86:87]
	v_pk_mul_f32 v[88:89], v[88:89], v[160:161] op_sel_hi:[1,0]
	v_pk_mul_f32 v[90:91], v[90:91], v[160:161] op_sel_hi:[1,0]
	v_pk_mul_f32 v[80:81], v[80:81], v[160:161] op_sel_hi:[1,0]
	v_pk_mul_f32 v[82:83], v[82:83], v[160:161] op_sel_hi:[1,0]
	v_exp_f32_e32 v88, v88
	v_exp_f32_e32 v89, v89
	v_exp_f32_e32 v90, v90
	v_exp_f32_e32 v91, v91
	v_exp_f32_e32 v80, v80
	v_exp_f32_e32 v81, v81
	v_exp_f32_e32 v82, v82
	v_exp_f32_e32 v83, v83
	v_fma_f32 v88, v88, v186, v186
	v_fma_f32 v89, v89, v186, v186
	v_fma_f32 v90, v90, v186, v186
	v_fma_f32 v91, v91, v186, v186
	v_fma_f32 v80, v80, v186, v186
	v_fma_f32 v81, v81, v186, v186
	v_fma_f32 v82, v82, v186, v186
	v_fma_f32 v83, v83, v186, v186
	v_rcp_f32_e32 v88, v88
	v_rcp_f32_e32 v89, v89
	v_rcp_f32_e32 v90, v90
	v_rcp_f32_e32 v91, v91
	v_rcp_f32_e32 v80, v80
	v_rcp_f32_e32 v81, v81
	v_rcp_f32_e32 v82, v82
	v_rcp_f32_e32 v83, v83
	v_lshl_add_u64 v[150:151], v[148:149], 0, s[100:101]
	v_pk_mul_f32 v[92:93], v[92:93], v[88:89]
	v_pk_mul_f32 v[94:95], v[94:95], v[90:91]
	v_pk_mul_f32 v[84:85], v[84:85], v[80:81]
	v_pk_mul_f32 v[86:87], v[86:87], v[82:83]
	s_nop 0
	v_cvt_pk_bf16_f32 v136, v92, v93
	v_cvt_pk_bf16_f32 v137, v94, v95
	v_cvt_pk_bf16_f32 v138, v84, v85
	v_cvt_pk_bf16_f32 v139, v86, v87
	global_store_dwordx4 v[148:149], v[136:139], off
	v_pk_mul_f32 v[76:77], v[72:73], v[76:77]
	v_pk_mul_f32 v[78:79], v[74:75], v[78:79]
	v_pk_mul_f32 v[68:69], v[64:65], v[68:69]
	v_pk_mul_f32 v[70:71], v[66:67], v[70:71]
	v_pk_mul_f32 v[72:73], v[72:73], v[164:165] op_sel_hi:[1,0]
	v_pk_mul_f32 v[74:75], v[74:75], v[164:165] op_sel_hi:[1,0]
	v_pk_mul_f32 v[64:65], v[64:65], v[164:165] op_sel_hi:[1,0]
	v_pk_mul_f32 v[66:67], v[66:67], v[164:165] op_sel_hi:[1,0]
	v_exp_f32_e32 v72, v72
	v_exp_f32_e32 v73, v73
	v_exp_f32_e32 v74, v74
	v_exp_f32_e32 v75, v75
	v_exp_f32_e32 v64, v64
	v_exp_f32_e32 v65, v65
	v_exp_f32_e32 v66, v66
	v_exp_f32_e32 v67, v67
	v_fma_f32 v72, v72, v187, v187
	v_fma_f32 v73, v73, v187, v187
	v_fma_f32 v74, v74, v187, v187
	v_fma_f32 v75, v75, v187, v187
	v_fma_f32 v64, v64, v187, v187
	v_fma_f32 v65, v65, v187, v187
	v_fma_f32 v66, v66, v187, v187
	v_fma_f32 v67, v67, v187, v187
	v_rcp_f32_e32 v72, v72
	v_rcp_f32_e32 v73, v73
	v_rcp_f32_e32 v74, v74
	v_rcp_f32_e32 v75, v75
	v_rcp_f32_e32 v64, v64
	v_rcp_f32_e32 v65, v65
	v_rcp_f32_e32 v66, v66
	v_rcp_f32_e32 v67, v67
	v_lshl_add_u64 v[148:149], v[150:151], 0, s[0:1]
	v_pk_mul_f32 v[76:77], v[76:77], v[72:73]
	v_pk_mul_f32 v[78:79], v[78:79], v[74:75]
	v_pk_mul_f32 v[68:69], v[68:69], v[64:65]
	v_pk_mul_f32 v[70:71], v[70:71], v[66:67]
	s_nop 0
	v_cvt_pk_bf16_f32 v140, v76, v77
	v_cvt_pk_bf16_f32 v141, v78, v79
	v_cvt_pk_bf16_f32 v142, v68, v69
	v_cvt_pk_bf16_f32 v143, v70, v71
	global_store_dwordx4 v[150:151], v[140:143], off
	v_pk_mul_f32 v[60:61], v[56:57], v[60:61]
	v_pk_mul_f32 v[62:63], v[58:59], v[62:63]
	v_pk_mul_f32 v[52:53], v[48:49], v[52:53]
	v_pk_mul_f32 v[54:55], v[50:51], v[54:55]
	v_pk_mul_f32 v[56:57], v[56:57], v[168:169] op_sel_hi:[1,0]
	v_pk_mul_f32 v[58:59], v[58:59], v[168:169] op_sel_hi:[1,0]
	v_pk_mul_f32 v[48:49], v[48:49], v[168:169] op_sel_hi:[1,0]
	v_pk_mul_f32 v[50:51], v[50:51], v[168:169] op_sel_hi:[1,0]
	v_exp_f32_e32 v56, v56
	v_exp_f32_e32 v57, v57
	v_exp_f32_e32 v58, v58
	v_exp_f32_e32 v59, v59
	v_exp_f32_e32 v48, v48
	v_exp_f32_e32 v49, v49
	v_exp_f32_e32 v50, v50
	v_exp_f32_e32 v51, v51
; __device__ __forceinline__ unsigned cvt_pk_bf16(float lo, float hi) { unsigned r; asm volatile("v_cvt_pk_bf16_f32 %0, %1, %2" : "=v"(r) : "v"(lo), "v"(hi)); return r; }
; __device__ __forceinline__ float fast_sigmoid(float x) { return __builtin_amdgcn_rcpf(1.0f + __expf(-x)); }
;     __device__ __forceinline__ void operator()(const f32x4 (&acc)[2][2][4][2], const pg8::Unit& u, int wr, int wc, int fr_, int fq_, LAS const unsigned char* xl) const {
;     ...
;                     } else {
;                         bf16_t* rowp = O + (size_t)row * ldc + u.pn * 128 + wc * 32 + 8 * fq;
;                         float a[8];
; #pragma unroll
;                         for (int n = 0; n < 2; ++n)
; #pragma unroll
;                             for (int j = 0; j < 4; ++j) { const float g = acc[ai][0][m][n][j] * rinv, up = acc[ai][1][m][n][j] * rinv; a[4 * n + j] = g * fast_sigmoid(g) * up; }
;                         u32x4 w; w.x = pg8::cvt_pk_bf16(a[0], a[1]); w.y = pg8::cvt_pk_bf16(a[2], a[3]); w.z = pg8::cvt_pk_bf16(a[4], a[5]); w.w = pg8::cvt_pk_bf16(a[6], a[7]);
;                         *(u32x4*)rowp = w;
	v_fma_f32 v56, v56, v188, v188
	v_fma_f32 v57, v57, v188, v188
	v_fma_f32 v58, v58, v188, v188
	v_fma_f32 v59, v59, v188, v188
	v_fma_f32 v48, v48, v188, v188
	v_fma_f32 v49, v49, v188, v188
	v_fma_f32 v50, v50, v188, v188
	v_fma_f32 v51, v51, v188, v188
	v_rcp_f32_e32 v56, v56
	v_rcp_f32_e32 v57, v57
	v_rcp_f32_e32 v58, v58
	v_rcp_f32_e32 v59, v59
	v_rcp_f32_e32 v48, v48
	v_rcp_f32_e32 v49, v49
	v_rcp_f32_e32 v50, v50
	v_rcp_f32_e32 v51, v51
	v_lshl_add_u64 v[150:151], v[148:149], 0, s[100:101]
	v_pk_mul_f32 v[60:61], v[60:61], v[56:57]
	v_pk_mul_f32 v[62:63], v[62:63], v[58:59]
	v_pk_mul_f32 v[52:53], v[52:53], v[48:49]
	v_pk_mul_f32 v[54:55], v[54:55], v[50:51]
	s_nop 0
	v_cvt_pk_bf16_f32 v136, v60, v61
	v_cvt_pk_bf16_f32 v137, v62, v63
	v_cvt_pk_bf16_f32 v138, v52, v53
	v_cvt_pk_bf16_f32 v139, v54, v55
	global_store_dwordx4 v[148:149], v[136:139], off
	v_pk_mul_f32 v[44:45], v[40:41], v[44:45]
	v_pk_mul_f32 v[46:47], v[42:43], v[46:47]
	v_pk_mul_f32 v[36:37], v[32:33], v[36:37]
	v_pk_mul_f32 v[38:39], v[34:35], v[38:39]
	v_pk_mul_f32 v[40:41], v[40:41], v[172:173] op_sel_hi:[1,0]
	v_pk_mul_f32 v[42:43], v[42:43], v[172:173] op_sel_hi:[1,0]
	v_pk_mul_f32 v[32:33], v[32:33], v[172:173] op_sel_hi:[1,0]
	v_pk_mul_f32 v[34:35], v[34:35], v[172:173] op_sel_hi:[1,0]
	v_exp_f32_e32 v40, v40
	v_exp_f32_e32 v41, v41
	v_exp_f32_e32 v42, v42
	v_exp_f32_e32 v43, v43
	v_exp_f32_e32 v32, v32
	v_exp_f32_e32 v33, v33
	v_exp_f32_e32 v34, v34
	v_exp_f32_e32 v35, v35
	v_fma_f32 v40, v40, v189, v189
	v_fma_f32 v41, v41, v189, v189
	v_fma_f32 v42, v42, v189, v189
	v_fma_f32 v43, v43, v189, v189
	v_fma_f32 v32, v32, v189, v189
	v_fma_f32 v33, v33, v189, v189
	v_fma_f32 v34, v34, v189, v189
	v_fma_f32 v35, v35, v189, v189
	v_rcp_f32_e32 v40, v40
	v_rcp_f32_e32 v41, v41
	v_rcp_f32_e32 v42, v42
	v_rcp_f32_e32 v43, v43
	v_rcp_f32_e32 v32, v32
	v_rcp_f32_e32 v33, v33
	v_rcp_f32_e32 v34, v34
	v_rcp_f32_e32 v35, v35
	v_lshl_add_u64 v[148:149], v[150:151], 0, s[100:101]
	v_pk_mul_f32 v[44:45], v[44:45], v[40:41]
	v_pk_mul_f32 v[46:47], v[46:47], v[42:43]
	v_pk_mul_f32 v[36:37], v[36:37], v[32:33]
	v_pk_mul_f32 v[38:39], v[38:39], v[34:35]
	s_nop 0
	v_cvt_pk_bf16_f32 v140, v44, v45
	v_cvt_pk_bf16_f32 v141, v46, v47
	v_cvt_pk_bf16_f32 v142, v36, v37
	v_cvt_pk_bf16_f32 v143, v38, v39
	global_store_dwordx4 v[150:151], v[140:143], off
	v_pk_mul_f32 v[28:29], v[24:25], v[28:29]
	v_pk_mul_f32 v[30:31], v[26:27], v[30:31]
	v_pk_mul_f32 v[20:21], v[16:17], v[20:21]
	v_pk_mul_f32 v[22:23], v[18:19], v[22:23]
	v_pk_mul_f32 v[24:25], v[24:25], v[176:177] op_sel_hi:[1,0]
	v_pk_mul_f32 v[26:27], v[26:27], v[176:177] op_sel_hi:[1,0]
	v_pk_mul_f32 v[16:17], v[16:17], v[176:177] op_sel_hi:[1,0]
	v_pk_mul_f32 v[18:19], v[18:19], v[176:177] op_sel_hi:[1,0]
	v_exp_f32_e32 v24, v24
	v_exp_f32_e32 v25, v25
	v_exp_f32_e32 v26, v26
	v_exp_f32_e32 v27, v27
	v_exp_f32_e32 v16, v16
	v_exp_f32_e32 v17, v17
	v_exp_f32_e32 v18, v18
	v_exp_f32_e32 v19, v19
	v_fma_f32 v24, v24, v190, v190
	v_fma_f32 v25, v25, v190, v190
	v_fma_f32 v26, v26, v190, v190
	v_fma_f32 v27, v27, v190, v190
	v_fma_f32 v16, v16, v190, v190
	v_fma_f32 v17, v17, v190, v190
	v_fma_f32 v18, v18, v190, v190
	v_fma_f32 v19, v19, v190, v190
	v_rcp_f32_e32 v24, v24
	v_rcp_f32_e32 v25, v25
	v_rcp_f32_e32 v26, v26
	v_rcp_f32_e32 v27, v27
	v_rcp_f32_e32 v16, v16
	v_rcp_f32_e32 v17, v17
	v_rcp_f32_e32 v18, v18
	v_rcp_f32_e32 v19, v19
	v_lshl_add_u64 v[150:151], v[148:149], 0, s[100:101]
	v_pk_mul_f32 v[28:29], v[28:29], v[24:25]
	v_pk_mul_f32 v[30:31], v[30:31], v[26:27]
	v_pk_mul_f32 v[20:21], v[20:21], v[16:17]
	v_pk_mul_f32 v[22:23], v[22:23], v[18:19]
	s_nop 0
	v_cvt_pk_bf16_f32 v136, v28, v29
	v_cvt_pk_bf16_f32 v137, v30, v31
	v_cvt_pk_bf16_f32 v138, v20, v21
	v_cvt_pk_bf16_f32 v139, v22, v23
	global_store_dwordx4 v[148:149], v[136:139], off
	v_pk_mul_f32 v[12:13], v[8:9], v[12:13]
	v_pk_mul_f32 v[14:15], v[10:11], v[14:15]
	v_pk_mul_f32 v[0:1], v[4:5], v[0:1]
	v_pk_mul_f32 v[2:3], v[6:7], v[2:3]
	v_pk_mul_f32 v[8:9], v[8:9], v[180:181] op_sel_hi:[1,0]
	v_pk_mul_f32 v[10:11], v[10:11], v[180:181] op_sel_hi:[1,0]
	v_pk_mul_f32 v[4:5], v[4:5], v[180:181] op_sel_hi:[1,0]
	v_pk_mul_f32 v[6:7], v[6:7], v[180:181] op_sel_hi:[1,0]
	v_exp_f32_e32 v8, v8
	v_exp_f32_e32 v9, v9
	v_exp_f32_e32 v10, v10
	v_exp_f32_e32 v11, v11
	v_exp_f32_e32 v4, v4
	v_exp_f32_e32 v5, v5
	v_exp_f32_e32 v6, v6
	v_exp_f32_e32 v7, v7
	v_fma_f32 v8, v8, v191, v191
	v_fma_f32 v9, v9, v191, v191
	v_fma_f32 v10, v10, v191, v191
	v_fma_f32 v11, v11, v191, v191
	v_fma_f32 v4, v4, v191, v191
	v_fma_f32 v5, v5, v191, v191
	v_fma_f32 v6, v6, v191, v191
	v_fma_f32 v7, v7, v191, v191
	v_rcp_f32_e32 v8, v8
	v_rcp_f32_e32 v9, v9
	v_rcp_f32_e32 v10, v10
	v_rcp_f32_e32 v11, v11
	v_rcp_f32_e32 v4, v4
	v_rcp_f32_e32 v5, v5
	v_rcp_f32_e32 v6, v6
	v_rcp_f32_e32 v7, v7
	v_pk_mul_f32 v[12:13], v[12:13], v[8:9]
	v_pk_mul_f32 v[14:15], v[14:15], v[10:11]
	v_pk_mul_f32 v[0:1], v[0:1], v[4:5]
	v_pk_mul_f32 v[2:3], v[2:3], v[6:7]
	s_nop 0
	v_cvt_pk_bf16_f32 v140, v12, v13
	v_cvt_pk_bf16_f32 v141, v14, v15
	v_cvt_pk_bf16_f32 v142, v0, v1
	v_cvt_pk_bf16_f32 v143, v2, v3
	global_store_dwordx4 v[150:151], v[140:143], off
	s_mov_b64 s[0:1], -1
	s_cbranch_vccnz .LBB0_403
	s_andn2_b64 vcc, exec, s[20:21]
	s_cbranch_vccnz .LBB0_402
	s_barrier
	s_branch .LBB0_402
